# previous + retention: the serialized global loads of each chunk step (4 K-row loads of build_kt, 8 V-fragment loads of the state update) issued together with counted vmcnt waits
# speedup vs baseline: 1.0920x; 1.0066x over previous
; DI float bf2f(u16 v) { return __uint_as_float(((unsigned)v) << 16); }
; DI int ltid() { int t = __builtin_amdgcn_workitem_id_x(); asm volatile("" : "+v"(t)); return t; }
; DI void build_kt(char* kt, const u16* __restrict__ QK, int row0, int h, float lg2, bool fwd) {
;   const int tid = ltid();
; #pragma unroll
;   for (int j = 0; j < 4; ++j) {
;     const int idx = tid + 256 * j;
;     const int m = idx >> 3, dc = idx & 7;
;     const u32x4 raw = *(const u32x4*)(QK + (size_t)(row0 + m) * 1024 + 512 + h * 64 + dc * 8);
;     const float dec = exp2f(lg2 * (float)(fwd ? (127 - m) : m));
; #pragma unroll
;     for (int i = 0; i < 8; ++i) {
;       const u16 e = (u16)((i & 1) ? (raw[i >> 1] >> 16) : (raw[i >> 1] & 0xffffu));
;       const int d = dc * 8 + i;
;       *(u16*)(kt + d * 256 + ((((m >> 3) ^ (d & 15)) << 4) | ((m & 7) << 1))) = f2bf(bf2f(e) * dec);
;     }
;   }
; }
; DI void state_update(f32x16 (&S)[2], const char* kt, const u16* __restrict__ vt_rows  ,
;                      float cd, int lane) {
;   const int r = lane & 31, h5 = lane >> 5;
; #pragma unroll
;   for (int i = 0; i < 16; ++i) { S[0][i] *= cd; S[1][i] *= cd; }
.LBB0_473:
	s_and_b64 s[4:5], s[46:47], exec
	s_cselect_b32 s4, s34, s6
	v_mov_b32_e32 v34, v196
	s_barrier
	s_add_i32 s4, s88, s4
	v_ashrrev_i32_e32 v42, 3, v34
	v_add_u32_e32 v36, s4, v42
	v_lshlrev_b32_e32 v41, 3, v34
	v_ashrrev_i32_e32 v37, 31, v36
	v_and_b32_e32 v35, 56, v41
	v_lshlrev_b64 v[36:37], 11, v[36:37]
	v_lshl_add_u64 v[36:37], s[42:43], 0, v[36:37]
	v_lshlrev_b32_e32 v0, 1, v35
	v_lshl_add_u64 v[36:37], v[36:37], 0, v[0:1]
	v_add_co_u32_e32 v110, vcc, 0x10000, v36
	s_nop 1
	v_addc_co_u32_e32 v111, vcc, 0, v37, vcc
	global_load_dwordx4 v[52:55], v[36:37], off offset:1024
	global_load_dwordx4 v[76:79], v[110:111], off offset:1024
	v_add_co_u32_e32 v110, vcc, 0x10000, v110
	s_nop 1
	v_addc_co_u32_e32 v111, vcc, 0, v111, vcc
	global_load_dwordx4 v[80:83], v[110:111], off offset:1024
	v_add_co_u32_e32 v110, vcc, 0x10000, v110
	s_nop 1
	v_addc_co_u32_e32 v111, vcc, 0, v111, vcc
	global_load_dwordx4 v[84:87], v[110:111], off offset:1024
	v_cvt_f32_i32_e32 v36, v42
	v_lshlrev_b32_e32 v42, 1, v42
	v_and_b32_e32 v57, 14, v42
	v_pk_mul_f32 v[2:3], v[38:39], v[2:3]
	v_mul_f32_e32 v37, v170, v36
	v_cmp_gt_f32_e32 vcc, s13, v37
	v_pk_mul_f32 v[18:19], v[38:39], v[18:19]
	v_pk_mul_f32 v[4:5], v[38:39], v[4:5]
	v_cndmask_b32_e32 v37, 0, v203, vcc
	v_fmac_f32_e32 v37, v170, v36
	v_exp_f32_e32 v36, v37
	v_cndmask_b32_e32 v37, 0, v204, vcc
	v_pk_mul_f32 v[20:21], v[38:39], v[20:21]
	v_pk_mul_f32 v[6:7], v[38:39], v[6:7]
	v_ldexp_f32 v36, v36, v37
	v_ashrrev_i32_e32 v37, 6, v34
	v_bitop3_b32 v44, v41, v37, 8 bitop3:0x6c
	v_pk_mul_f32 v[22:23], v[38:39], v[22:23]
	v_pk_mul_f32 v[8:9], v[38:39], v[8:9]
	v_pk_mul_f32 v[24:25], v[38:39], v[24:25]
	v_pk_mul_f32 v[10:11], v[38:39], v[10:11]
	v_pk_mul_f32 v[26:27], v[38:39], v[26:27]
	v_pk_mul_f32 v[12:13], v[38:39], v[12:13]
	v_pk_mul_f32 v[28:29], v[38:39], v[28:29]
	v_pk_mul_f32 v[14:15], v[38:39], v[14:15]
	v_pk_mul_f32 v[30:31], v[38:39], v[30:31]
	v_pk_mul_f32 v[16:17], v[38:39], v[16:17]
	v_pk_mul_f32 v[32:33], v[38:39], v[32:33]
	s_waitcnt vmcnt(3)
	v_lshlrev_b32_e32 v42, 16, v52
	v_mul_f32_e32 v42, v36, v42
	v_cvt_pk_bf16_f32 v43, v42, s0
	v_lshlrev_b32_e32 v42, 8, v35
	v_lshl_add_u32 v44, v44, 4, v42
	v_or_b32_e32 v44, v44, v57
	ds_write_b16 v44, v43 offset:32768
	v_or_b32_e32 v43, 1, v35
	v_and_b32_e32 v44, 0xffff0000, v52
	v_lshlrev_b32_e32 v45, 8, v43
	v_bitop3_b32 v46, v43, v37, 9 bitop3:0x6c
	v_mul_f32_e32 v44, v36, v44
	v_lshl_add_u32 v46, v46, 4, v45
	v_cvt_pk_bf16_f32 v44, v44, s0
	v_or_b32_e32 v46, v46, v57
	ds_write_b16 v46, v44 offset:32768
	v_lshlrev_b32_e32 v46, 16, v53
	v_or_b32_e32 v44, 2, v35
	v_mul_f32_e32 v46, v36, v46
	v_cvt_pk_bf16_f32 v47, v46, s0
	v_lshlrev_b32_e32 v46, 8, v44
	v_bitop3_b32 v48, v44, v37, 10 bitop3:0x6c
	v_lshl_add_u32 v48, v48, 4, v46
	v_or_b32_e32 v48, v48, v57
	ds_write_b16 v48, v47 offset:32768
	v_or_b32_e32 v47, 3, v35
	v_and_b32_e32 v48, 0xffff0000, v53
	v_lshlrev_b32_e32 v49, 8, v47
	v_bitop3_b32 v50, v47, v37, 11 bitop3:0x6c
	v_mul_f32_e32 v48, v36, v48
	v_lshl_add_u32 v50, v50, 4, v49
	v_cvt_pk_bf16_f32 v48, v48, s0
	v_or_b32_e32 v50, v50, v57
	ds_write_b16 v50, v48 offset:32768
	v_lshlrev_b32_e32 v50, 16, v54
	v_or_b32_e32 v48, 4, v35
	v_mul_f32_e32 v50, v36, v50
	v_cvt_pk_bf16_f32 v51, v50, s0
	v_lshlrev_b32_e32 v50, 8, v48
	v_bitop3_b32 v52, v48, v37, 12 bitop3:0x6c
	v_lshl_add_u32 v52, v52, 4, v50
	v_or_b32_e32 v52, v52, v57
	ds_write_b16 v52, v51 offset:32768
	v_or_b32_e32 v51, 5, v35
	v_and_b32_e32 v52, 0xffff0000, v54
	v_lshlrev_b32_e32 v53, 8, v51
	v_bitop3_b32 v54, v51, v37, 13 bitop3:0x6c
	v_mul_f32_e32 v52, v36, v52
	v_lshl_add_u32 v54, v54, 4, v53
	v_cvt_pk_bf16_f32 v52, v52, s0
	v_or_b32_e32 v54, v54, v57
	ds_write_b16 v54, v52 offset:32768
	v_lshlrev_b32_e32 v54, 16, v55
	v_or_b32_e32 v52, 6, v35
	v_mul_f32_e32 v54, v36, v54
	v_cvt_pk_bf16_f32 v56, v54, s0
	v_lshlrev_b32_e32 v54, 8, v52
	v_bitop3_b32 v58, v52, v37, 14 bitop3:0x6c
	v_lshl_add_u32 v58, v58, 4, v54
	v_or_b32_e32 v58, v58, v57
	ds_write_b16 v58, v56 offset:32768
	v_and_b32_e32 v56, 0xffff0000, v55
	v_or_b32_e32 v55, 7, v35
	v_mul_f32_e32 v35, v36, v56
	v_lshlrev_b32_e32 v56, 8, v55
	v_bitop3_b32 v36, v55, v37, 15 bitop3:0x6c
	v_lshl_add_u32 v36, v36, 4, v56
	v_cvt_pk_bf16_f32 v35, v35, s0
	v_or_b32_e32 v36, v36, v57
	ds_write_b16 v36, v35 offset:32768
	v_add_u32_e32 v35, 0x100, v34
	v_ashrrev_i32_e32 v57, 3, v35
	v_add_u32_e32 v36, s4, v57
	v_ashrrev_i32_e32 v37, 31, v36
	v_lshlrev_b64 v[36:37], 11, v[36:37]
	v_lshl_add_u64 v[36:37], s[42:43], 0, v[36:37]
	v_lshl_add_u64 v[36:37], v[36:37], 0, v[0:1]
	v_cvt_f32_i32_e32 v36, v57
	v_ashrrev_i32_e32 v35, 6, v35
	v_bitop3_b32 v62, v41, v35, 8 bitop3:0x6c
	v_lshl_add_u32 v62, v62, 4, v42
	v_mul_f32_e32 v37, v170, v36
	v_cmp_gt_f32_e32 vcc, s13, v37
	s_nop 1
	v_cndmask_b32_e32 v37, 0, v203, vcc
	v_fmac_f32_e32 v37, v170, v36
	v_exp_f32_e32 v36, v37
	v_cndmask_b32_e32 v37, 0, v204, vcc
	v_ldexp_f32 v36, v36, v37
	v_lshlrev_b32_e32 v37, 1, v57
	v_and_b32_e32 v37, 14, v37
	v_or_b32_e32 v62, v62, v37
	s_waitcnt vmcnt(2)
; DI float bf2f(u16 v) { return __uint_as_float(((unsigned)v) << 16); }
; DI void build_kt(char* kt, const u16* __restrict__ QK, int row0, int h, float lg2, bool fwd) {
;     ...
;   for (int j = 0; j < 4; ++j) {
;     const int idx = tid + 256 * j;
;     const int m = idx >> 3, dc = idx & 7;
;     const u32x4 raw = *(const u32x4*)(QK + (size_t)(row0 + m) * 1024 + 512 + h * 64 + dc * 8);
;     const float dec = exp2f(lg2 * (float)(fwd ? (127 - m) : m));
; #pragma unroll
;     for (int i = 0; i < 8; ++i) {
;       const u16 e = (u16)((i & 1) ? (raw[i >> 1] >> 16) : (raw[i >> 1] & 0xffffu));
;       const int d = dc * 8 + i;
;       *(u16*)(kt + d * 256 + ((((m >> 3) ^ (d & 15)) << 4) | ((m & 7) << 1))) = f2bf(bf2f(e) * dec);
;     }
	v_lshlrev_b32_e32 v57, 16, v76
	v_mul_f32_e32 v57, v36, v57
	v_cvt_pk_bf16_f32 v57, v57, s0
	ds_write_b16 v62, v57 offset:32768
	v_and_b32_e32 v57, 0xffff0000, v76
	v_bitop3_b32 v58, v43, v35, 9 bitop3:0x6c
	v_mul_f32_e32 v57, v36, v57
	v_lshl_add_u32 v58, v58, 4, v45
	v_cvt_pk_bf16_f32 v57, v57, s0
	v_or_b32_e32 v58, v58, v37
	ds_write_b16 v58, v57 offset:32768
	v_lshlrev_b32_e32 v57, 16, v77
	v_bitop3_b32 v58, v44, v35, 10 bitop3:0x6c
	v_mul_f32_e32 v57, v36, v57
	v_lshl_add_u32 v58, v58, 4, v46
	v_cvt_pk_bf16_f32 v57, v57, s0
	v_or_b32_e32 v58, v58, v37
	ds_write_b16 v58, v57 offset:32768
	v_and_b32_e32 v57, 0xffff0000, v77
	v_bitop3_b32 v58, v47, v35, 11 bitop3:0x6c
	v_mul_f32_e32 v57, v36, v57
	v_lshl_add_u32 v58, v58, 4, v49
	v_cvt_pk_bf16_f32 v57, v57, s0
	v_or_b32_e32 v58, v58, v37
	ds_write_b16 v58, v57 offset:32768
	v_lshlrev_b32_e32 v57, 16, v78
	v_bitop3_b32 v58, v48, v35, 12 bitop3:0x6c
	v_mul_f32_e32 v57, v36, v57
	v_lshl_add_u32 v58, v58, 4, v50
	v_cvt_pk_bf16_f32 v57, v57, s0
	v_or_b32_e32 v58, v58, v37
	ds_write_b16 v58, v57 offset:32768
	v_and_b32_e32 v57, 0xffff0000, v78
	v_bitop3_b32 v58, v51, v35, 13 bitop3:0x6c
	v_mul_f32_e32 v57, v36, v57
	v_lshl_add_u32 v58, v58, 4, v53
	v_cvt_pk_bf16_f32 v57, v57, s0
	v_or_b32_e32 v58, v58, v37
	ds_write_b16 v58, v57 offset:32768
	v_lshlrev_b32_e32 v57, 16, v79
	v_bitop3_b32 v58, v52, v35, 14 bitop3:0x6c
	v_mul_f32_e32 v57, v36, v57
	v_lshl_add_u32 v58, v58, 4, v54
	v_cvt_pk_bf16_f32 v57, v57, s0
	v_or_b32_e32 v58, v58, v37
	ds_write_b16 v58, v57 offset:32768
	v_and_b32_e32 v57, 0xffff0000, v79
	v_bitop3_b32 v35, v55, v35, 15 bitop3:0x6c
	v_mul_f32_e32 v36, v36, v57
	v_lshl_add_u32 v35, v35, 4, v56
	v_cvt_pk_bf16_f32 v36, v36, s0
	v_or_b32_e32 v35, v35, v37
	ds_write_b16 v35, v36 offset:32768
	v_add_u32_e32 v35, 0x200, v34
	v_ashrrev_i32_e32 v57, 3, v35
	v_add_u32_e32 v36, s4, v57
	v_ashrrev_i32_e32 v37, 31, v36
	v_lshlrev_b64 v[36:37], 11, v[36:37]
	v_lshl_add_u64 v[36:37], s[42:43], 0, v[36:37]
	v_lshl_add_u64 v[36:37], v[36:37], 0, v[0:1]
	v_cvt_f32_i32_e32 v36, v57
	v_ashrrev_i32_e32 v35, 6, v35
	v_bitop3_b32 v62, v41, v35, 8 bitop3:0x6c
	v_lshl_add_u32 v62, v62, 4, v42
	v_mul_f32_e32 v37, v170, v36
	v_cmp_gt_f32_e32 vcc, s13, v37
	s_nop 1
	v_cndmask_b32_e32 v37, 0, v203, vcc
	v_fmac_f32_e32 v37, v170, v36
	v_exp_f32_e32 v36, v37
	v_cndmask_b32_e32 v37, 0, v204, vcc
	v_ldexp_f32 v36, v36, v37
	v_lshlrev_b32_e32 v37, 1, v57
	v_and_b32_e32 v37, 14, v37
	v_or_b32_e32 v62, v62, v37
	s_waitcnt vmcnt(1)
	v_lshlrev_b32_e32 v57, 16, v80
	v_mul_f32_e32 v57, v36, v57
	v_cvt_pk_bf16_f32 v57, v57, s0
	ds_write_b16 v62, v57 offset:32768
	v_and_b32_e32 v57, 0xffff0000, v80
	v_bitop3_b32 v58, v43, v35, 9 bitop3:0x6c
	v_mul_f32_e32 v57, v36, v57
	v_lshl_add_u32 v58, v58, 4, v45
	v_cvt_pk_bf16_f32 v57, v57, s0
	v_or_b32_e32 v58, v58, v37
	ds_write_b16 v58, v57 offset:32768
	v_lshlrev_b32_e32 v57, 16, v81
	v_bitop3_b32 v58, v44, v35, 10 bitop3:0x6c
	v_mul_f32_e32 v57, v36, v57
	v_lshl_add_u32 v58, v58, 4, v46
	v_cvt_pk_bf16_f32 v57, v57, s0
	v_or_b32_e32 v58, v58, v37
	ds_write_b16 v58, v57 offset:32768
	v_and_b32_e32 v57, 0xffff0000, v81
	v_bitop3_b32 v58, v47, v35, 11 bitop3:0x6c
	v_mul_f32_e32 v57, v36, v57
	v_lshl_add_u32 v58, v58, 4, v49
	v_cvt_pk_bf16_f32 v57, v57, s0
	v_or_b32_e32 v58, v58, v37
	ds_write_b16 v58, v57 offset:32768
	v_lshlrev_b32_e32 v57, 16, v82
	v_bitop3_b32 v58, v48, v35, 12 bitop3:0x6c
	v_mul_f32_e32 v57, v36, v57
	v_lshl_add_u32 v58, v58, 4, v50
	v_cvt_pk_bf16_f32 v57, v57, s0
	v_or_b32_e32 v58, v58, v37
	ds_write_b16 v58, v57 offset:32768
	v_and_b32_e32 v57, 0xffff0000, v82
	v_bitop3_b32 v58, v51, v35, 13 bitop3:0x6c
	v_mul_f32_e32 v57, v36, v57
	v_lshl_add_u32 v58, v58, 4, v53
	v_cvt_pk_bf16_f32 v57, v57, s0
	v_or_b32_e32 v58, v58, v37
	ds_write_b16 v58, v57 offset:32768
	v_lshlrev_b32_e32 v57, 16, v83
	v_bitop3_b32 v58, v52, v35, 14 bitop3:0x6c
	v_mul_f32_e32 v57, v36, v57
	v_lshl_add_u32 v58, v58, 4, v54
	v_cvt_pk_bf16_f32 v57, v57, s0
	v_or_b32_e32 v58, v58, v37
	ds_write_b16 v58, v57 offset:32768
	v_and_b32_e32 v57, 0xffff0000, v83
	v_mul_f32_e32 v36, v36, v57
	v_bitop3_b32 v35, v55, v35, 15 bitop3:0x6c
	v_add_u32_e32 v57, 0x300, v34
	v_lshl_add_u32 v35, v35, 4, v56
	v_ashrrev_i32_e32 v58, 3, v57
	v_cvt_pk_bf16_f32 v36, v36, s0
	v_or_b32_e32 v35, v35, v37
	v_add_u32_e32 v34, s4, v58
	ds_write_b16 v35, v36 offset:32768
	v_ashrrev_i32_e32 v35, 31, v34
	v_lshlrev_b64 v[34:35], 11, v[34:35]
	v_lshl_add_u64 v[34:35], s[42:43], 0, v[34:35]
	v_lshl_add_u64 v[34:35], v[34:35], 0, v[0:1]
	v_cvt_f32_i32_e32 v0, v58
	v_ashrrev_i32_e32 v57, 6, v57
	v_lshlrev_b32_e32 v58, 1, v58
	v_bitop3_b32 v41, v41, v57, 8 bitop3:0x6c
	v_mul_f32_e32 v59, v170, v0
	v_cmp_gt_f32_e32 vcc, s13, v59
	v_and_b32_e32 v58, 14, v58
	v_lshl_add_u32 v41, v41, 4, v42
	v_cndmask_b32_e32 v59, 0, v203, vcc
	v_fmac_f32_e32 v59, v170, v0
	v_exp_f32_e32 v0, v59
	v_cndmask_b32_e32 v59, 0, v204, vcc
	v_or_b32_e32 v41, v41, v58
	v_ldexp_f32 v0, v0, v59
	s_waitcnt vmcnt(0)
; DI float bf2f(u16 v) { return __uint_as_float(((unsigned)v) << 16); }
; #define MFMA32(a, b, c) __builtin_amdgcn_mfma_f32_32x32x16_bf16((a), (b), (c), 0, 0, 0)
; DI void build_kt(char* kt, const u16* __restrict__ QK, int row0, int h, float lg2, bool fwd) {
;     ...
;     for (int i = 0; i < 8; ++i) {
;       const u16 e = (u16)((i & 1) ? (raw[i >> 1] >> 16) : (raw[i >> 1] & 0xffffu));
;       const int d = dc * 8 + i;
;       *(u16*)(kt + d * 256 + ((((m >> 3) ^ (d & 15)) << 4) | ((m & 7) << 1))) = f2bf(bf2f(e) * dec);
;     }
;   }
; }
; DI void state_update(f32x16 (&S)[2], const char* kt, const u16* __restrict__ vt_rows  ,
;                      float cd, int lane) {
;   const int r = lane & 31, h5 = lane >> 5;
; #pragma unroll
;   for (int i = 0; i < 16; ++i) { S[0][i] *= cd; S[1][i] *= cd; }
; #pragma unroll
;   for (int s = 0; s < 8; ++s) {
;     const bf16x8 bv = *(const bf16x8*)(vt_rows + (size_t)r * VT_LD + s * 16 + h5 * 8);
;     const int ch = 2 * s + h5;
;     const bf16x8 a0 = *(const bf16x8*)(kt + r * 256 + ((ch ^ (r & 15)) << 4));
;     const bf16x8 a1 = *(const bf16x8*)(kt + (32 + r) * 256 + ((ch ^ (r & 15)) << 4));
;     S[0] = MFMA32(a0, bv, S[0]);
;     S[1] = MFMA32(a1, bv, S[1]);
;   }
; }
	v_lshlrev_b32_e32 v59, 16, v84
	v_mul_f32_e32 v59, v0, v59
	v_cvt_pk_bf16_f32 v59, v59, s0
	ds_write_b16 v41, v59 offset:32768
	v_and_b32_e32 v34, 0xffff0000, v84
	v_bitop3_b32 v41, v43, v57, 9 bitop3:0x6c
	v_mul_f32_e32 v34, v0, v34
	v_lshl_add_u32 v41, v41, 4, v45
	v_cvt_pk_bf16_f32 v34, v34, s0
	v_or_b32_e32 v41, v41, v58
	ds_write_b16 v41, v34 offset:32768
	v_lshlrev_b32_e32 v34, 16, v85
	v_bitop3_b32 v41, v44, v57, 10 bitop3:0x6c
	v_mul_f32_e32 v34, v0, v34
	v_lshl_add_u32 v41, v41, 4, v46
	v_cvt_pk_bf16_f32 v34, v34, s0
	v_or_b32_e32 v41, v41, v58
	ds_write_b16 v41, v34 offset:32768
	v_and_b32_e32 v34, 0xffff0000, v85
	v_bitop3_b32 v35, v47, v57, 11 bitop3:0x6c
	v_mul_f32_e32 v34, v0, v34
	v_lshl_add_u32 v35, v35, 4, v49
	v_cvt_pk_bf16_f32 v34, v34, s0
	v_or_b32_e32 v35, v35, v58
	ds_write_b16 v35, v34 offset:32768
	v_lshlrev_b32_e32 v34, 16, v86
	v_bitop3_b32 v35, v48, v57, 12 bitop3:0x6c
	v_mul_f32_e32 v34, v0, v34
	v_lshl_add_u32 v35, v35, 4, v50
	v_cvt_pk_bf16_f32 v34, v34, s0
	v_or_b32_e32 v35, v35, v58
	ds_write_b16 v35, v34 offset:32768
	v_and_b32_e32 v34, 0xffff0000, v86
	v_bitop3_b32 v35, v51, v57, 13 bitop3:0x6c
	v_mul_f32_e32 v34, v0, v34
	v_lshl_add_u32 v35, v35, 4, v53
	v_cvt_pk_bf16_f32 v34, v34, s0
	v_or_b32_e32 v35, v35, v58
	ds_write_b16 v35, v34 offset:32768
	v_lshlrev_b32_e32 v34, 16, v87
	v_bitop3_b32 v35, v52, v57, 14 bitop3:0x6c
	v_mul_f32_e32 v34, v0, v34
	v_lshl_add_u32 v35, v35, 4, v54
	v_cvt_pk_bf16_f32 v34, v34, s0
	v_or_b32_e32 v35, v35, v58
	ds_write_b16 v35, v34 offset:32768
	v_and_b32_e32 v34, 0xffff0000, v87
	v_mul_f32_e32 v0, v0, v34
	v_bitop3_b32 v34, v55, v57, 15 bitop3:0x6c
	v_lshl_add_u32 v34, v34, 4, v56
	v_cvt_pk_bf16_f32 v0, v0, s0
	v_or_b32_e32 v34, v34, v58
	v_ashrrev_i32_e32 v41, 5, v168
	ds_write_b16 v34, v0 offset:32768
	v_lshlrev_b32_e32 v34, 3, v41
	v_ashrrev_i32_e32 v35, 31, v34
	v_lshlrev_b32_e32 v0, 5, v169
	v_and_b32_e32 v36, 31, v168
	v_lshlrev_b64 v[34:35], 1, v[34:35]
	v_mul_u32_u24_e32 v37, 0x900, v36
	v_mad_i64_i32 v[34:35], s[4:5], v0, s12, v[34:35]
	v_lshlrev_b32_e32 v0, 1, v37
	s_add_u32 s4, s44, s0
	v_lshl_add_u64 v[34:35], v[34:35], 0, v[0:1]
	s_addc_u32 s5, s45, s1
	v_lshl_add_u64 v[34:35], s[4:5], 0, v[34:35]
	s_mov_b32 s4, 0xb361000
	v_add_co_u32_e32 v34, vcc, s4, v34
	s_waitcnt lgkmcnt(0)
	s_nop 0
	v_addc_co_u32_e32 v35, vcc, 0, v35, vcc
	s_barrier
	global_load_dwordx4 v[76:79], v[34:35], off offset:256
	global_load_dwordx4 v[80:83], v[34:35], off offset:288
	global_load_dwordx4 v[84:87], v[34:35], off offset:320
	global_load_dwordx4 v[88:91], v[34:35], off offset:352
	global_load_dwordx4 v[92:95], v[34:35], off offset:384
	global_load_dwordx4 v[96:99], v[34:35], off offset:416
	global_load_dwordx4 v[100:103], v[34:35], off offset:448
	global_load_dwordx4 v[104:107], v[34:35], off offset:480
	v_lshlrev_b32_e32 v0, 8, v36
	v_bitop3_b32 v36, v41, v168, 15 bitop3:0x78
	v_lshl_add_u32 v36, v36, 4, v0
	ds_read_b128 v[46:49], v36 offset:32768
	ds_read_b128 v[50:53], v36 offset:40960
	s_waitcnt vmcnt(7) lgkmcnt(1)
	v_mfma_f32_32x32x16_bf16 v[2:17], v[46:49], v[76:79], v[2:17]
	v_add_u32_e32 v36, 2, v41
	v_bitop3_b32 v36, v36, v168, 15 bitop3:0x78
	v_lshl_add_u32 v36, v36, 4, v0
	s_waitcnt lgkmcnt(0)
	v_mfma_f32_32x32x16_bf16 v[18:33], v[50:53], v[76:79], v[18:33]
	ds_read_b128 v[46:49], v36 offset:32768
	ds_read_b128 v[50:53], v36 offset:40960
	v_add_u32_e32 v36, 4, v41
	v_bitop3_b32 v36, v36, v168, 15 bitop3:0x78
	v_lshl_add_u32 v36, v36, 4, v0
	s_waitcnt vmcnt(6) lgkmcnt(1)
	v_mfma_f32_32x32x16_bf16 v[2:17], v[46:49], v[80:83], v[2:17]
	s_waitcnt lgkmcnt(0)
	v_mfma_f32_32x32x16_bf16 v[18:33], v[50:53], v[80:83], v[18:33]
	ds_read_b128 v[46:49], v36 offset:32768
	ds_read_b128 v[50:53], v36 offset:40960
	v_add_u32_e32 v36, 6, v41
	v_bitop3_b32 v36, v36, v168, 15 bitop3:0x78
	v_lshl_add_u32 v36, v36, 4, v0
	s_waitcnt vmcnt(5) lgkmcnt(1)
	v_mfma_f32_32x32x16_bf16 v[2:17], v[46:49], v[84:87], v[2:17]
	s_waitcnt lgkmcnt(0)
	v_mfma_f32_32x32x16_bf16 v[18:33], v[50:53], v[84:87], v[18:33]
	ds_read_b128 v[46:49], v36 offset:32768
	ds_read_b128 v[50:53], v36 offset:40960
	v_add_u32_e32 v36, 8, v41
	v_bitop3_b32 v36, v36, v168, 15 bitop3:0x78
	v_lshl_add_u32 v36, v36, 4, v0
	s_waitcnt vmcnt(4) lgkmcnt(1)
	v_mfma_f32_32x32x16_bf16 v[2:17], v[46:49], v[88:91], v[2:17]
	s_waitcnt lgkmcnt(0)
	v_mfma_f32_32x32x16_bf16 v[18:33], v[50:53], v[88:91], v[18:33]
	ds_read_b128 v[46:49], v36 offset:32768
	ds_read_b128 v[50:53], v36 offset:40960
	v_add_u32_e32 v36, 10, v41
	v_bitop3_b32 v36, v36, v168, 15 bitop3:0x78
	v_lshl_add_u32 v36, v36, 4, v0
	s_waitcnt vmcnt(3) lgkmcnt(1)
	v_mfma_f32_32x32x16_bf16 v[2:17], v[46:49], v[92:95], v[2:17]
	s_waitcnt lgkmcnt(0)
	v_mfma_f32_32x32x16_bf16 v[18:33], v[50:53], v[92:95], v[18:33]
	ds_read_b128 v[46:49], v36 offset:32768
	ds_read_b128 v[50:53], v36 offset:40960
	v_add_u32_e32 v36, 12, v41
	v_bitop3_b32 v36, v36, v168, 15 bitop3:0x78
	v_lshl_add_u32 v36, v36, 4, v0
	v_add_u32_e32 v41, 14, v41
	v_bitop3_b32 v41, v41, v168, 15 bitop3:0x78
	s_waitcnt vmcnt(2) lgkmcnt(1)
	v_mfma_f32_32x32x16_bf16 v[2:17], v[46:49], v[96:99], v[2:17]
	v_lshl_add_u32 v0, v41, 4, v0
	s_waitcnt lgkmcnt(0)
	v_mfma_f32_32x32x16_bf16 v[18:33], v[50:53], v[96:99], v[18:33]
	ds_read_b128 v[46:49], v36 offset:32768
	ds_read_b128 v[50:53], v36 offset:40960
	s_waitcnt vmcnt(1) lgkmcnt(1)
	v_mfma_f32_32x32x16_bf16 v[2:17], v[46:49], v[100:103], v[2:17]
	s_waitcnt lgkmcnt(0)
	v_mfma_f32_32x32x16_bf16 v[18:33], v[50:53], v[100:103], v[18:33]
	ds_read_b128 v[42:45], v0 offset:32768
	ds_read_b128 v[46:49], v0 offset:40960
	s_waitcnt vmcnt(0) lgkmcnt(1)
	v_mfma_f32_32x32x16_bf16 v[2:17], v[42:45], v[104:107], v[2:17]
	s_waitcnt lgkmcnt(0)
	v_mfma_f32_32x32x16_bf16 v[18:33], v[46:49], v[104:107], v[18:33]

; #define MFMA32(a, b, c) __builtin_amdgcn_mfma_f32_32x32x16_bf16((a), (b), (c), 0, 0, 0)
; DI void state_update(f32x16 (&S)[2], const char* kt, const u16* __restrict__ vt_rows  ,
;                      float cd, int lane) {
;   const int r = lane & 31, h5 = lane >> 5;
; #pragma unroll
;   for (int i = 0; i < 16; ++i) { S[0][i] *= cd; S[1][i] *= cd; }
; #pragma unroll
;   for (int s = 0; s < 8; ++s) {
;     const bf16x8 bv = *(const bf16x8*)(vt_rows + (size_t)r * VT_LD + s * 16 + h5 * 8);
;     const int ch = 2 * s + h5;
;     const bf16x8 a0 = *(const bf16x8*)(kt + r * 256 + ((ch ^ (r & 15)) << 4));
;     const bf16x8 a1 = *(const bf16x8*)(kt + (32 + r) * 256 + ((ch ^ (r & 15)) << 4));
;     S[0] = MFMA32(a0, bv, S[0]);
;     S[1] = MFMA32(a1, bv, S[1]);
;   }
; }
.LBB0_483:
	v_mov_b64_e32 v[34:35], s[46:47]
	v_mad_i64_i32 v[34:35], s[0:1], v174, s12, v[34:35]
	v_lshl_add_u64 v[34:35], s[94:95], 1, v[34:35]
	v_lshl_add_u64 v[34:35], v[0:1], 1, v[34:35]
	v_lshl_add_u64 v[34:35], v[132:133], 1, v[34:35]
	global_load_dwordx4 v[76:79], v[34:35], off
	global_load_dwordx4 v[80:83], v[34:35], off offset:32
	global_load_dwordx4 v[84:87], v[34:35], off offset:64
	global_load_dwordx4 v[88:91], v[34:35], off offset:96
	global_load_dwordx4 v[92:95], v[34:35], off offset:128
	global_load_dwordx4 v[96:99], v[34:35], off offset:160
	global_load_dwordx4 v[100:103], v[34:35], off offset:192
	global_load_dwordx4 v[104:107], v[34:35], off offset:224
	v_lshlrev_b32_e32 v0, 8, v173
	v_xor_b32_e32 v44, v36, v172
	v_lshl_add_u32 v48, v44, 4, v0
	ds_read_b128 v[44:47], v48 offset:32768
	ds_read_b128 v[48:51], v48 offset:40960
	v_pk_mul_f32 v[2:3], v[130:131], v[2:3]
	v_pk_mul_f32 v[18:19], v[130:131], v[18:19]
	v_pk_mul_f32 v[4:5], v[130:131], v[4:5]
	v_pk_mul_f32 v[20:21], v[130:131], v[20:21]
	v_pk_mul_f32 v[6:7], v[130:131], v[6:7]
	v_pk_mul_f32 v[22:23], v[130:131], v[22:23]
	v_pk_mul_f32 v[8:9], v[130:131], v[8:9]
	v_pk_mul_f32 v[24:25], v[130:131], v[24:25]
	v_pk_mul_f32 v[10:11], v[130:131], v[10:11]
	v_pk_mul_f32 v[26:27], v[130:131], v[26:27]
	v_pk_mul_f32 v[12:13], v[130:131], v[12:13]
	v_pk_mul_f32 v[28:29], v[130:131], v[28:29]
	v_pk_mul_f32 v[14:15], v[130:131], v[14:15]
	v_pk_mul_f32 v[30:31], v[130:131], v[30:31]
	v_pk_mul_f32 v[16:17], v[130:131], v[16:17]
	v_pk_mul_f32 v[32:33], v[130:131], v[32:33]
	v_xor_b32_e32 v39, v36, v39
	v_lshl_add_u32 v39, v39, 4, v0
	v_xor_b32_e32 v38, v36, v38
	v_lshl_add_u32 v38, v38, 4, v0
	v_xor_b32_e32 v37, v36, v37
	v_lshl_add_u32 v37, v37, 4, v0
	s_add_i32 s5, s5, 1
	s_cmp_eq_u32 s5, 18
	s_cselect_b64 s[0:1], -1, 0
	s_waitcnt vmcnt(7) lgkmcnt(1)
	v_mfma_f32_32x32x16_bf16 v[2:17], v[44:47], v[76:79], v[2:17]
	s_waitcnt lgkmcnt(0)
	v_mfma_f32_32x32x16_bf16 v[18:33], v[48:51], v[76:79], v[18:33]
	ds_read_b128 v[44:47], v39 offset:32768
	ds_read_b128 v[48:51], v39 offset:40960
	s_waitcnt vmcnt(6) lgkmcnt(1)
	v_mfma_f32_32x32x16_bf16 v[2:17], v[44:47], v[80:83], v[2:17]
	s_waitcnt lgkmcnt(0)
	v_mfma_f32_32x32x16_bf16 v[18:33], v[48:51], v[80:83], v[18:33]
	ds_read_b128 v[44:47], v38 offset:32768
	ds_read_b128 v[48:51], v38 offset:40960
	s_waitcnt vmcnt(5) lgkmcnt(1)
	v_mfma_f32_32x32x16_bf16 v[2:17], v[44:47], v[84:87], v[2:17]
	s_waitcnt lgkmcnt(0)
	v_mfma_f32_32x32x16_bf16 v[18:33], v[48:51], v[84:87], v[18:33]
	ds_read_b128 v[42:45], v37 offset:32768
	ds_read_b128 v[46:49], v37 offset:40960
	v_add_u32_e32 v37, 8, v172
	v_xor_b32_e32 v37, v36, v37
	v_lshl_add_u32 v37, v37, 4, v0
	s_waitcnt vmcnt(4) lgkmcnt(1)
	v_mfma_f32_32x32x16_bf16 v[2:17], v[42:45], v[88:91], v[2:17]
	s_waitcnt lgkmcnt(0)
	v_mfma_f32_32x32x16_bf16 v[18:33], v[46:49], v[88:91], v[18:33]
	ds_read_b128 v[42:45], v37 offset:32768
	ds_read_b128 v[46:49], v37 offset:40960
	v_add_u32_e32 v37, 10, v172
	v_xor_b32_e32 v37, v36, v37
	v_lshl_add_u32 v37, v37, 4, v0
	s_waitcnt vmcnt(3) lgkmcnt(1)
	v_mfma_f32_32x32x16_bf16 v[2:17], v[42:45], v[92:95], v[2:17]
	s_waitcnt lgkmcnt(0)
	v_mfma_f32_32x32x16_bf16 v[18:33], v[46:49], v[92:95], v[18:33]
	ds_read_b128 v[42:45], v37 offset:32768
	ds_read_b128 v[46:49], v37 offset:40960
	v_add_u32_e32 v37, 12, v172
	v_xor_b32_e32 v37, v36, v37
	v_lshl_add_u32 v37, v37, 4, v0
	s_waitcnt vmcnt(2) lgkmcnt(1)
	v_mfma_f32_32x32x16_bf16 v[2:17], v[42:45], v[96:99], v[2:17]
	s_waitcnt lgkmcnt(0)
	v_mfma_f32_32x32x16_bf16 v[18:33], v[46:49], v[96:99], v[18:33]
	ds_read_b128 v[42:45], v37 offset:32768
	ds_read_b128 v[46:49], v37 offset:40960
	s_waitcnt vmcnt(1) lgkmcnt(1)
	v_mfma_f32_32x32x16_bf16 v[2:17], v[42:45], v[100:103], v[2:17]
	s_waitcnt lgkmcnt(0)
	v_mfma_f32_32x32x16_bf16 v[18:33], v[46:49], v[100:103], v[18:33]
	v_add_u32_e32 v34, 14, v172
	v_xor_b32_e32 v34, v36, v34
	v_lshl_add_u32 v0, v34, 4, v0
	ds_read_b128 v[34:37], v0 offset:32768
	ds_read_b128 v[42:45], v0 offset:40960
	s_waitcnt vmcnt(0) lgkmcnt(1)
	v_mfma_f32_32x32x16_bf16 v[2:17], v[34:37], v[104:107], v[2:17]
	s_waitcnt lgkmcnt(0)
	v_mfma_f32_32x32x16_bf16 v[18:33], v[42:45], v[104:107], v[18:33]
	s_and_b64 vcc, exec, s[0:1]
	s_cbranch_vccnz .LBB0_467
; DI float bf2f(u16 v) { return __uint_as_float(((unsigned)v) << 16); }
; DI unsigned pack2(float a, float b) { f32x2_t v = {a, b}; bf16x2_t r = __builtin_convertvector(v, bf16x2_t); return __builtin_bit_cast(unsigned, r); }
; DI int ltid() { int t = __builtin_amdgcn_workitem_id_x(); asm volatile("" : "+v"(t)); return t; }
; DI void build_kt(char* kt, const u16* __restrict__ QK, int row0, int h, float lg2, bool fwd) {
;   const int tid = ltid();
; #pragma unroll
;   for (int j = 0; j < 4; ++j) {
;     const int idx = tid + 256 * j;
;     const int m = idx >> 3, dc = idx & 7;
;     const u32x4 raw = *(const u32x4*)(QK + (size_t)(row0 + m) * 1024 + 512 + h * 64 + dc * 8);
;     const float dec = exp2f(lg2 * (float)(fwd ? (127 - m) : m));
; #pragma unroll
;     for (int i = 0; i < 8; ++i) {
;       const u16 e = (u16)((i & 1) ? (raw[i >> 1] >> 16) : (raw[i >> 1] & 0xffffu));
;       const int d = dc * 8 + i;
;       *(u16*)(kt + d * 256 + ((((m >> 3) ^ (d & 15)) << 4) | ((m & 7) << 1))) = f2bf(bf2f(e) * dec);
;     }
;   }
; }
; DI void retention_item(const Params& p, int l, bool ctx_out, int item2, char* smem) {
;     ...
;     __syncthreads();
;     {
;       const int e = w * 32 + r;
; #pragma unroll
;       for (int dt = 0; dt < 2; ++dt)
; #pragma unroll
;         for (int q = 0; q < 4; ++q) {
;           const int d = dt * 32 + 8 * q + 4 * h5;
;           *(u32x2*)(stf + e * 128 + ((((d >> 3) ^ ((e >> 1) & 7)) << 4) | ((d & 7) << 1))) =
;               mk2(pack2(S[dt][4 * q], S[dt][4 * q + 1]), pack2(S[dt][4 * q + 2], S[dt][4 * q + 3]));
;         }
;     }
.LBB0_484:
	s_cmp_lt_u32 s5, 2
	s_cselect_b32 s15, 16, -2
	s_add_i32 s15, s15, s5
	s_cmp_lt_i32 s15, 16
	s_cselect_b64 s[0:1], -1, 0
	s_cmp_gt_i32 s15, s4
	s_cselect_b64 s[68:69], -1, 0
	s_and_b64 s[68:69], s[0:1], s[68:69]
	s_and_b64 vcc, exec, s[68:69]
	s_cbranch_vccnz .LBB0_489
	v_cvt_pk_bf16_f32 v34, v2, v3
	v_ashrrev_i32_e32 v172, 5, v168
	v_and_b32_e32 v173, 31, v168
	v_lshlrev_b32_e32 v174, 5, v169
	v_lshlrev_b32_e32 v132, 3, v172
	v_or_b32_e32 v179, v174, v173
	v_lshrrev_b32_e32 v0, 1, v168
	v_and_b32_e32 v38, 8, v132
	v_bfe_u32 v63, v172, 1, 29
	v_lshl_or_b32 v36, v179, 7, v38
	v_bitop3_b32 v37, v63, v0, 7 bitop3:0x78
	v_cvt_pk_bf16_f32 v35, v4, v5
	v_lshl_add_u32 v37, v37, 4, v36
	v_add_u32_e32 v62, 1, v63
	s_barrier
	ds_write_b64 v37, v[34:35] offset:49152
	v_bitop3_b32 v37, v62, v0, 7 bitop3:0x78
	v_cvt_pk_bf16_f32 v34, v6, v7
	v_cvt_pk_bf16_f32 v35, v8, v9
	v_lshl_add_u32 v37, v37, 4, v36
	v_add_u32_e32 v61, 2, v63
	ds_write_b64 v37, v[34:35] offset:49152
	v_bitop3_b32 v37, v61, v0, 7 bitop3:0x78
	v_lshlrev_b32_e32 v54, 2, v172
	v_cvt_pk_bf16_f32 v34, v10, v11
	v_cvt_pk_bf16_f32 v35, v12, v13
	v_lshl_add_u32 v37, v37, 4, v36
	v_add_u32_e32 v60, 3, v63
	ds_write_b64 v37, v[34:35] offset:49152
	v_bitop3_b32 v37, v60, v0, 7 bitop3:0x78
	v_add_u32_e32 v59, 32, v54
	v_cvt_pk_bf16_f32 v34, v14, v15
	v_cvt_pk_bf16_f32 v35, v16, v17
	v_lshl_add_u32 v37, v37, 4, v36
	v_lshrrev_b32_e32 v58, 3, v59
	ds_write_b64 v37, v[34:35] offset:49152
	v_bitop3_b32 v37, v58, v0, 7 bitop3:0x78
	v_cvt_pk_bf16_f32 v34, v18, v19
	v_cvt_pk_bf16_f32 v35, v20, v21
	v_lshl_add_u32 v37, v37, 4, v36
	v_add_u32_e32 v57, 1, v58
	ds_write_b64 v37, v[34:35] offset:49152
	v_bitop3_b32 v37, v57, v0, 7 bitop3:0x78
	s_and_b64 s[68:69], s[0:1], exec
	v_cvt_pk_bf16_f32 v34, v22, v23
	v_cvt_pk_bf16_f32 v35, v24, v25
	v_lshl_add_u32 v37, v37, 4, v36
	v_add_u32_e32 v56, 2, v58
	s_cselect_b32 s14, s34, s6
	s_ashr_i32 s9, s15, 2
	s_add_i32 s70, s15, -16
	ds_write_b64 v37, v[34:35] offset:49152
	v_bitop3_b32 v37, v56, v0, 7 bitop3:0x78
	v_add_u32_e32 v55, 3, v58
	s_and_b64 s[68:69], s[0:1], exec
	v_cvt_pk_bf16_f32 v34, v26, v27
	v_cvt_pk_bf16_f32 v35, v28, v29
	v_lshl_add_u32 v37, v37, 4, v36
	v_bitop3_b32 v0, v55, v0, 7 bitop3:0x78
	s_cselect_b32 s9, s9, s70
	ds_write_b64 v37, v[34:35] offset:49152
	v_cvt_pk_bf16_f32 v34, v30, v31
	v_cvt_pk_bf16_f32 v35, v32, v33
	v_lshl_add_u32 v0, v0, 4, v36
	s_lshl_b32 s94, s15, 7
	v_mov_b32_e32 v65, v196
	ds_write_b64 v0, v[34:35] offset:49152
	s_add_i32 s14, s14, s94
	s_nor_b64 s[88:89], s[26:27], s[0:1]
	v_ashrrev_i32_e32 v40, 3, v65
	v_add_u32_e32 v34, s14, v40
	v_lshlrev_b32_e32 v39, 3, v65
	v_ashrrev_i32_e32 v35, 31, v34
	v_and_b32_e32 v53, 56, v39
	v_lshlrev_b64 v[34:35], 11, v[34:35]
	v_lshl_add_u64 v[34:35], s[42:43], 0, v[34:35]
	v_lshlrev_b32_e32 v0, 1, v53
	v_lshl_add_u64 v[34:35], v[34:35], 0, v[0:1]
	v_add_co_u32_e32 v110, vcc, 0x10000, v34
	s_nop 1
	v_addc_co_u32_e32 v111, vcc, 0, v35, vcc
	global_load_dwordx4 v[34:37], v[34:35], off offset:1024
	global_load_dwordx4 v[76:79], v[110:111], off offset:1024
	v_add_co_u32_e32 v110, vcc, 0x10000, v110
	s_nop 1
	v_addc_co_u32_e32 v111, vcc, 0, v111, vcc
	global_load_dwordx4 v[80:83], v[110:111], off offset:1024
	v_add_co_u32_e32 v110, vcc, 0x10000, v110
	s_nop 1
	v_addc_co_u32_e32 v111, vcc, 0, v111, vcc
	global_load_dwordx4 v[84:87], v[110:111], off offset:1024
	v_sub_u32_e32 v41, 0x7f, v40
	v_cvt_f32_i32_e32 v41, v41
	v_lshlrev_b32_e32 v40, 1, v40
	v_and_b32_e32 v67, 14, v40
	v_ashrrev_i32_e32 v66, 6, v65
	v_mul_f32_e32 v42, v171, v41
	v_cmp_gt_f32_e32 vcc, s13, v42
	v_or_b32_e32 v46, 4, v53
	v_lshlrev_b32_e32 v48, 8, v46
	v_cndmask_b32_e32 v42, 0, v203, vcc
	v_fmac_f32_e32 v42, v171, v41
	v_exp_f32_e32 v41, v42
	v_cndmask_b32_e32 v42, 0, v204, vcc
	v_or_b32_e32 v49, 5, v53
	v_lshlrev_b32_e32 v51, 8, v49
	v_ldexp_f32 v64, v41, v42
	v_bitop3_b32 v42, v39, v66, 8 bitop3:0x6c
	v_or_b32_e32 v50, 6, v53
	v_lshlrev_b32_e32 v52, 8, v50
	s_cmp_lg_u32 s9, s39
	s_cselect_b64 s[68:69], -1, 0
	s_or_b64 s[88:89], s[88:89], s[68:69]
	v_ashrrev_i32_e32 v133, 31, v132
	s_waitcnt vmcnt(3)
	v_lshlrev_b32_e32 v40, 16, v34
	v_mul_f32_e32 v40, v64, v40
	v_cvt_pk_bf16_f32 v41, v40, s0
	v_lshlrev_b32_e32 v40, 8, v53
	v_lshl_add_u32 v42, v42, 4, v40
	v_or_b32_e32 v42, v42, v67
	ds_write_b16 v42, v41 offset:32768
	v_or_b32_e32 v41, 1, v53
	v_and_b32_e32 v34, 0xffff0000, v34
	v_lshlrev_b32_e32 v43, 8, v41
	v_bitop3_b32 v42, v41, v66, 9 bitop3:0x6c
	v_mul_f32_e32 v34, v64, v34
	v_lshl_add_u32 v42, v42, 4, v43
	v_cvt_pk_bf16_f32 v34, v34, s0
	v_or_b32_e32 v42, v42, v67
	ds_write_b16 v42, v34 offset:32768
	v_or_b32_e32 v42, 2, v53
	v_lshlrev_b32_e32 v34, 16, v35
	v_lshlrev_b32_e32 v44, 8, v42
	v_bitop3_b32 v45, v42, v66, 10 bitop3:0x6c
	v_mul_f32_e32 v34, v64, v34
	v_lshl_add_u32 v45, v45, 4, v44
	v_cvt_pk_bf16_f32 v34, v34, s0
	v_or_b32_e32 v45, v45, v67
	ds_write_b16 v45, v34 offset:32768
	v_or_b32_e32 v45, 3, v53
	v_and_b32_e32 v34, 0xffff0000, v35
	v_lshlrev_b32_e32 v47, 8, v45
	v_bitop3_b32 v35, v45, v66, 11 bitop3:0x6c
	v_mul_f32_e32 v34, v64, v34
	v_lshl_add_u32 v35, v35, 4, v47
	v_cvt_pk_bf16_f32 v34, v34, s0
	v_or_b32_e32 v35, v35, v67
	ds_write_b16 v35, v34 offset:32768
	v_lshlrev_b32_e32 v34, 16, v36
	v_bitop3_b32 v35, v46, v66, 12 bitop3:0x6c
	v_mul_f32_e32 v34, v64, v34
	v_lshl_add_u32 v35, v35, 4, v48
	v_cvt_pk_bf16_f32 v34, v34, s0
	v_or_b32_e32 v35, v35, v67
	ds_write_b16 v35, v34 offset:32768
	v_and_b32_e32 v34, 0xffff0000, v36
	v_bitop3_b32 v35, v49, v66, 13 bitop3:0x6c
	v_mul_f32_e32 v34, v64, v34
	v_lshl_add_u32 v35, v35, 4, v51
	v_cvt_pk_bf16_f32 v34, v34, s0
	v_or_b32_e32 v35, v35, v67
	ds_write_b16 v35, v34 offset:32768
	v_lshlrev_b32_e32 v34, 16, v37
	v_bitop3_b32 v35, v50, v66, 14 bitop3:0x6c
	v_mul_f32_e32 v34, v64, v34
	v_lshl_add_u32 v35, v35, 4, v52
	v_cvt_pk_bf16_f32 v34, v34, s0
	v_or_b32_e32 v35, v35, v67
	ds_write_b16 v35, v34 offset:32768
	v_and_b32_e32 v34, 0xffff0000, v37
	v_or_b32_e32 v53, 7, v53
	v_mul_f32_e32 v34, v64, v34
	v_lshlrev_b32_e32 v64, 8, v53
	v_bitop3_b32 v35, v53, v66, 15 bitop3:0x6c
	v_lshl_add_u32 v35, v35, 4, v64
	v_add_u32_e32 v66, 0x100, v65
	v_cvt_pk_bf16_f32 v34, v34, s0
	v_or_b32_e32 v35, v35, v67
	v_ashrrev_i32_e32 v67, 3, v66
	ds_write_b16 v35, v34 offset:32768
	v_add_u32_e32 v34, s14, v67
	v_ashrrev_i32_e32 v35, 31, v34
	v_lshlrev_b64 v[34:35], 11, v[34:35]
	v_lshl_add_u64 v[34:35], s[42:43], 0, v[34:35]
	v_lshl_add_u64 v[34:35], v[34:35], 0, v[0:1]
	v_sub_u32_e32 v68, 0x7f, v67
	v_cvt_f32_i32_e32 v68, v68
	v_ashrrev_i32_e32 v66, 6, v66
	v_lshlrev_b32_e32 v67, 1, v67
	v_bitop3_b32 v70, v39, v66, 8 bitop3:0x6c
	v_mul_f32_e32 v69, v171, v68
	v_cmp_gt_f32_e32 vcc, s13, v69
	v_and_b32_e32 v67, 14, v67
	v_lshl_add_u32 v70, v70, 4, v40
	v_cndmask_b32_e32 v69, 0, v203, vcc
	v_fmac_f32_e32 v69, v171, v68
	v_exp_f32_e32 v68, v69
	v_cndmask_b32_e32 v69, 0, v204, vcc
	v_or_b32_e32 v70, v70, v67
	v_ldexp_f32 v68, v68, v69
	s_waitcnt vmcnt(2)
; DI float bf2f(u16 v) { return __uint_as_float(((unsigned)v) << 16); }
; DI void build_kt(char* kt, const u16* __restrict__ QK, int row0, int h, float lg2, bool fwd) {
;     ...
;   for (int j = 0; j < 4; ++j) {
;     const int idx = tid + 256 * j;
;     const int m = idx >> 3, dc = idx & 7;
;     const u32x4 raw = *(const u32x4*)(QK + (size_t)(row0 + m) * 1024 + 512 + h * 64 + dc * 8);
;     const float dec = exp2f(lg2 * (float)(fwd ? (127 - m) : m));
; #pragma unroll
;     for (int i = 0; i < 8; ++i) {
;       const u16 e = (u16)((i & 1) ? (raw[i >> 1] >> 16) : (raw[i >> 1] & 0xffffu));
;       const int d = dc * 8 + i;
;       *(u16*)(kt + d * 256 + ((((m >> 3) ^ (d & 15)) << 4) | ((m & 7) << 1))) = f2bf(bf2f(e) * dec);
;     }
	v_lshlrev_b32_e32 v69, 16, v76
	v_mul_f32_e32 v69, v68, v69
	v_cvt_pk_bf16_f32 v69, v69, s0
	ds_write_b16 v70, v69 offset:32768
	v_and_b32_e32 v34, 0xffff0000, v76
	v_bitop3_b32 v69, v41, v66, 9 bitop3:0x6c
	v_mul_f32_e32 v34, v68, v34
	v_lshl_add_u32 v69, v69, 4, v43
	v_cvt_pk_bf16_f32 v34, v34, s0
	v_or_b32_e32 v69, v69, v67
	ds_write_b16 v69, v34 offset:32768
	v_lshlrev_b32_e32 v34, 16, v77
	v_bitop3_b32 v69, v42, v66, 10 bitop3:0x6c
	v_mul_f32_e32 v34, v68, v34
	v_lshl_add_u32 v69, v69, 4, v44
	v_cvt_pk_bf16_f32 v34, v34, s0
	v_or_b32_e32 v69, v69, v67
	ds_write_b16 v69, v34 offset:32768
	v_and_b32_e32 v34, 0xffff0000, v77
	v_bitop3_b32 v35, v45, v66, 11 bitop3:0x6c
	v_mul_f32_e32 v34, v68, v34
	v_lshl_add_u32 v35, v35, 4, v47
	v_cvt_pk_bf16_f32 v34, v34, s0
	v_or_b32_e32 v35, v35, v67
	ds_write_b16 v35, v34 offset:32768
	v_lshlrev_b32_e32 v34, 16, v78
	v_bitop3_b32 v35, v46, v66, 12 bitop3:0x6c
	v_mul_f32_e32 v34, v68, v34
	v_lshl_add_u32 v35, v35, 4, v48
	v_cvt_pk_bf16_f32 v34, v34, s0
	v_or_b32_e32 v35, v35, v67
	ds_write_b16 v35, v34 offset:32768
	v_and_b32_e32 v34, 0xffff0000, v78
	v_bitop3_b32 v35, v49, v66, 13 bitop3:0x6c
	v_mul_f32_e32 v34, v68, v34
	v_lshl_add_u32 v35, v35, 4, v51
	v_cvt_pk_bf16_f32 v34, v34, s0
	v_or_b32_e32 v35, v35, v67
	ds_write_b16 v35, v34 offset:32768
	v_lshlrev_b32_e32 v34, 16, v79
	v_bitop3_b32 v35, v50, v66, 14 bitop3:0x6c
	v_mul_f32_e32 v34, v68, v34
	v_lshl_add_u32 v35, v35, 4, v52
	v_cvt_pk_bf16_f32 v34, v34, s0
	v_or_b32_e32 v35, v35, v67
	ds_write_b16 v35, v34 offset:32768
	v_and_b32_e32 v34, 0xffff0000, v79
	v_bitop3_b32 v35, v53, v66, 15 bitop3:0x6c
	v_mul_f32_e32 v34, v68, v34
	v_lshl_add_u32 v35, v35, 4, v64
	v_add_u32_e32 v66, 0x200, v65
	v_cvt_pk_bf16_f32 v34, v34, s0
	v_or_b32_e32 v35, v35, v67
	v_ashrrev_i32_e32 v67, 3, v66
	ds_write_b16 v35, v34 offset:32768
	v_add_u32_e32 v34, s14, v67
	v_ashrrev_i32_e32 v35, 31, v34
	v_lshlrev_b64 v[34:35], 11, v[34:35]
	v_lshl_add_u64 v[34:35], s[42:43], 0, v[34:35]
	v_lshl_add_u64 v[34:35], v[34:35], 0, v[0:1]
	v_sub_u32_e32 v68, 0x7f, v67
	v_cvt_f32_i32_e32 v68, v68
	v_ashrrev_i32_e32 v66, 6, v66
	v_lshlrev_b32_e32 v67, 1, v67
	v_bitop3_b32 v70, v39, v66, 8 bitop3:0x6c
	v_mul_f32_e32 v69, v171, v68
	v_cmp_gt_f32_e32 vcc, s13, v69
	v_and_b32_e32 v67, 14, v67
	v_lshl_add_u32 v70, v70, 4, v40
	v_cndmask_b32_e32 v69, 0, v203, vcc
	v_fmac_f32_e32 v69, v171, v68
	v_exp_f32_e32 v68, v69
	v_cndmask_b32_e32 v69, 0, v204, vcc
	v_or_b32_e32 v70, v70, v67
	v_add_u32_e32 v65, 0x300, v65
	v_ldexp_f32 v68, v68, v69
	s_waitcnt vmcnt(1)
	v_lshlrev_b32_e32 v69, 16, v80
	v_mul_f32_e32 v69, v68, v69
	v_cvt_pk_bf16_f32 v69, v69, s0
	ds_write_b16 v70, v69 offset:32768
	v_and_b32_e32 v34, 0xffff0000, v80
	v_bitop3_b32 v69, v41, v66, 9 bitop3:0x6c
	v_mul_f32_e32 v34, v68, v34
	v_lshl_add_u32 v69, v69, 4, v43
	v_cvt_pk_bf16_f32 v34, v34, s0
	v_or_b32_e32 v69, v69, v67
	ds_write_b16 v69, v34 offset:32768
	v_lshlrev_b32_e32 v34, 16, v81
	v_bitop3_b32 v69, v42, v66, 10 bitop3:0x6c
	v_mul_f32_e32 v34, v68, v34
	v_lshl_add_u32 v69, v69, 4, v44
	v_cvt_pk_bf16_f32 v34, v34, s0
	v_or_b32_e32 v69, v69, v67
	ds_write_b16 v69, v34 offset:32768
	v_and_b32_e32 v34, 0xffff0000, v81
	v_bitop3_b32 v35, v45, v66, 11 bitop3:0x6c
	v_mul_f32_e32 v34, v68, v34
	v_lshl_add_u32 v35, v35, 4, v47
	v_cvt_pk_bf16_f32 v34, v34, s0
	v_or_b32_e32 v35, v35, v67
	ds_write_b16 v35, v34 offset:32768
	v_lshlrev_b32_e32 v34, 16, v82
	v_bitop3_b32 v35, v46, v66, 12 bitop3:0x6c
	v_mul_f32_e32 v34, v68, v34
	v_lshl_add_u32 v35, v35, 4, v48
	v_cvt_pk_bf16_f32 v34, v34, s0
	v_or_b32_e32 v35, v35, v67
	ds_write_b16 v35, v34 offset:32768
	v_and_b32_e32 v34, 0xffff0000, v82
	v_bitop3_b32 v35, v49, v66, 13 bitop3:0x6c
	v_mul_f32_e32 v34, v68, v34
	v_lshl_add_u32 v35, v35, 4, v51
	v_cvt_pk_bf16_f32 v34, v34, s0
	v_or_b32_e32 v35, v35, v67
	ds_write_b16 v35, v34 offset:32768
	v_lshlrev_b32_e32 v34, 16, v83
	v_bitop3_b32 v35, v50, v66, 14 bitop3:0x6c
	v_mul_f32_e32 v34, v68, v34
	v_lshl_add_u32 v35, v35, 4, v52
	v_cvt_pk_bf16_f32 v34, v34, s0
	v_or_b32_e32 v35, v35, v67
	ds_write_b16 v35, v34 offset:32768
	v_and_b32_e32 v34, 0xffff0000, v83
	v_bitop3_b32 v35, v53, v66, 15 bitop3:0x6c
	v_mul_f32_e32 v34, v68, v34
	v_lshl_add_u32 v35, v35, 4, v64
	v_cvt_pk_bf16_f32 v34, v34, s0
	v_or_b32_e32 v35, v35, v67
	v_ashrrev_i32_e32 v66, 3, v65
	ds_write_b16 v35, v34 offset:32768
	v_add_u32_e32 v34, s14, v66
	v_ashrrev_i32_e32 v35, 31, v34
	v_lshlrev_b64 v[34:35], 11, v[34:35]
	v_lshl_add_u64 v[34:35], s[42:43], 0, v[34:35]
	v_lshl_add_u64 v[34:35], v[34:35], 0, v[0:1]
	v_sub_u32_e32 v0, 0x7f, v66
	v_cvt_f32_i32_e32 v0, v0
	v_ashrrev_i32_e32 v65, 6, v65
	v_lshlrev_b32_e32 v66, 1, v66
	v_bitop3_b32 v39, v39, v65, 8 bitop3:0x6c
	v_mul_f32_e32 v67, v171, v0
	v_cmp_gt_f32_e32 vcc, s13, v67
	v_and_b32_e32 v66, 14, v66
	v_lshl_add_u32 v39, v39, 4, v40
	v_cndmask_b32_e32 v67, 0, v203, vcc
	v_fmac_f32_e32 v67, v171, v0
	v_exp_f32_e32 v0, v67
	v_cndmask_b32_e32 v67, 0, v204, vcc
	v_or_b32_e32 v39, v39, v66
	s_and_b64 vcc, exec, s[88:89]
	v_ldexp_f32 v0, v0, v67
	s_waitcnt vmcnt(0)
	v_lshlrev_b32_e32 v67, 16, v84
	v_mul_f32_e32 v67, v0, v67
	v_cvt_pk_bf16_f32 v67, v67, s0
	ds_write_b16 v39, v67 offset:32768
	v_and_b32_e32 v34, 0xffff0000, v84
	v_bitop3_b32 v39, v41, v65, 9 bitop3:0x6c
	v_mul_f32_e32 v34, v0, v34
	v_lshl_add_u32 v39, v39, 4, v43
	v_cvt_pk_bf16_f32 v34, v34, s0
	v_or_b32_e32 v39, v39, v66
	ds_write_b16 v39, v34 offset:32768
	v_lshlrev_b32_e32 v34, 16, v85
	v_bitop3_b32 v39, v42, v65, 10 bitop3:0x6c
	v_mul_f32_e32 v34, v0, v34
	v_lshl_add_u32 v39, v39, 4, v44
	v_cvt_pk_bf16_f32 v34, v34, s0
	v_or_b32_e32 v39, v39, v66
	ds_write_b16 v39, v34 offset:32768
	v_and_b32_e32 v34, 0xffff0000, v85
	v_bitop3_b32 v35, v45, v65, 11 bitop3:0x6c
	v_mul_f32_e32 v34, v0, v34
	v_lshl_add_u32 v35, v35, 4, v47
	v_cvt_pk_bf16_f32 v34, v34, s0
	v_or_b32_e32 v35, v35, v66
	ds_write_b16 v35, v34 offset:32768
	v_lshlrev_b32_e32 v34, 16, v86
	v_bitop3_b32 v35, v46, v65, 12 bitop3:0x6c
	v_mul_f32_e32 v34, v0, v34
	v_lshl_add_u32 v35, v35, 4, v48
	v_cvt_pk_bf16_f32 v34, v34, s0
	v_or_b32_e32 v35, v35, v66
	ds_write_b16 v35, v34 offset:32768
	v_and_b32_e32 v34, 0xffff0000, v86
	v_bitop3_b32 v35, v49, v65, 13 bitop3:0x6c
	v_mul_f32_e32 v34, v0, v34
	v_lshl_add_u32 v35, v35, 4, v51
	v_cvt_pk_bf16_f32 v34, v34, s0
	v_or_b32_e32 v35, v35, v66
	ds_write_b16 v35, v34 offset:32768
	v_lshlrev_b32_e32 v34, 16, v87
	v_bitop3_b32 v35, v50, v65, 14 bitop3:0x6c
	v_mul_f32_e32 v34, v0, v34
	v_lshl_add_u32 v35, v35, 4, v52
	v_cvt_pk_bf16_f32 v34, v34, s0
	v_or_b32_e32 v35, v35, v66
	ds_write_b16 v35, v34 offset:32768
	v_and_b32_e32 v34, 0xffff0000, v87
	v_mul_f32_e32 v0, v0, v34
	v_bitop3_b32 v34, v53, v65, 15 bitop3:0x6c
	v_lshl_add_u32 v34, v34, 4, v64
	v_cvt_pk_bf16_f32 v0, v0, s0
	v_or_b32_e32 v34, v34, v66
	ds_write_b16 v34, v0 offset:32768
	s_cbranch_vccnz .LBB0_487
; DI unsigned pack2(float a, float b) { f32x2_t v = {a, b}; bf16x2_t r = __builtin_convertvector(v, bf16x2_t); return __builtin_bit_cast(unsigned, r); }
; #define MFMA32(a, b, c) __builtin_amdgcn_mfma_f32_32x32x16_bf16((a), (b), (c), 0, 0, 0)
; DI void retention_item(const Params& p, int l, bool ctx_out, int item2, char* smem) {
;     ...
;     if (outp) {
;       const int n = w * 32 + r;
; #pragma unroll
;       for (int s = 0; s < 4; ++s) qf[s] = *(const bf16x8*)(QK + (size_t)(row0 + n) * 1024 + h * 64 + s * 16 + h5 * 8);
; #pragma unroll
;       for (int mt = 0; mt < 4; ++mt) {
;         f32x16 a;
; #pragma unroll
;         for (int i = 0; i < 16; ++i) a[i] = 0.f;
; #pragma unroll
;         for (int s = 0; s < 4; ++s) {
;           const bf16x8 kf = *(const bf16x8*)(QK + (size_t)(row0 + mt * 32 + r) * 1024 + 512 + h * 64 + s * 16 + h5 * 8);
;           a = MFMA32(kf, qf[s], a);
;         }
; #pragma unroll
;         for (int q = 0; q < 4; ++q) {
;           float o[4];
; #pragma unroll
;           for (int j = 0; j < 4; ++j) {
;             const int m = mt * 32 + 8 * q + 4 * h5 + j;
;             const float dd = (m <= n) ? __builtin_amdgcn_exp2f(lgf2 * (float)(n - m)) : __builtin_amdgcn_exp2f(lgb2 * (float)(m - n));
;             o[j] = a[4 * q + j] * dd;
;           }
;           const int m0 = mt * 32 + 8 * q + 4 * h5;
;           *(u32x2*)(att + n * 256 + ((((m0 >> 3) ^ (n & 15)) << 4) | ((m0 & 7) << 1))) = mk2(pack2(o[0], o[1]), pack2(o[2], o[3]));
;         }
;       }
	v_add_u32_e32 v34, s14, v179
	v_ashrrev_i32_e32 v35, 31, v34
	v_lshlrev_b64 v[34:35], 11, v[34:35]
	v_lshl_add_u64 v[34:35], s[42:43], 0, v[34:35]
	v_lshlrev_b64 v[50:51], 1, v[132:133]
	v_or_b32_e32 v52, s14, v173
	v_lshl_add_u64 v[34:35], v[34:35], 0, v[50:51]
	v_ashrrev_i32_e32 v53, 31, v52
	global_load_dwordx4 v[114:117], v[34:35], off
	global_load_dwordx4 v[118:121], v[34:35], off offset:32
	global_load_dwordx4 v[122:125], v[34:35], off offset:64
	global_load_dwordx4 v[126:129], v[34:35], off offset:96
	v_lshlrev_b64 v[34:35], 11, v[52:53]
	v_lshl_add_u64 v[34:35], s[42:43], 0, v[34:35]
	v_lshl_add_u64 v[68:69], v[34:35], 0, v[50:51]
	global_load_dwordx4 v[34:37], v[68:69], off offset:1024
	global_load_dwordx4 v[64:67], v[68:69], off offset:1056
	v_lshl_or_b32 v0, v179, 8, v38
	v_sub_u32_e32 v53, v54, v179
	v_cmp_gt_i32_e32 vcc, v54, v179
	s_waitcnt vmcnt(1)
	v_mfma_f32_32x32x16_bf16 v[34:49], v[34:37], v[114:117], 0
	s_waitcnt vmcnt(0)
	v_mfma_f32_32x32x16_bf16 v[34:49], v[64:67], v[118:121], v[34:49]
	global_load_dwordx4 v[64:67], v[68:69], off offset:1088
	s_waitcnt vmcnt(0)
	v_mfma_f32_32x32x16_bf16 v[34:49], v[64:67], v[122:125], v[34:49]
	global_load_dwordx4 v[64:67], v[68:69], off offset:1120
	s_waitcnt vmcnt(0)
	v_mfma_f32_32x32x16_bf16 v[34:49], v[64:67], v[126:129], v[34:49]
	v_sub_u32_e32 v64, 0, v53
	v_max_i32_e32 v53, v53, v64
	v_cvt_f32_u32_e32 v53, v53
	v_cndmask_b32_e32 v64, v171, v170, vcc
	v_cmp_lt_i32_e32 vcc, v54, v179
	v_mul_f32_e32 v53, v64, v53
	v_exp_f32_e32 v64, v53
	v_or_b32_e32 v53, 1, v54
	v_sub_u32_e32 v65, v53, v179
	v_sub_u32_e32 v53, v179, v53
	v_cndmask_b32_e32 v53, v65, v53, vcc
	v_cvt_f32_i32_e32 v53, v53
	v_cndmask_b32_e32 v65, v170, v171, vcc
	v_mul_f32_e32 v53, v65, v53
	v_exp_f32_e32 v65, v53
	v_or_b32_e32 v53, 2, v54
	v_cmp_gt_i32_e32 vcc, v53, v179
	v_sub_u32_e32 v53, v53, v179
	v_pk_mul_f32 v[34:35], v[64:65], v[34:35]
	v_sub_u32_e32 v64, 0, v53
	v_max_i32_e32 v53, v53, v64
	v_cvt_f32_u32_e32 v53, v53
	v_cndmask_b32_e32 v64, v171, v170, vcc
	v_cvt_pk_bf16_f32 v34, v34, v35
	v_mul_f32_e32 v53, v64, v53
	v_exp_f32_e32 v64, v53
	v_or_b32_e32 v53, 3, v54
	v_cmp_gt_i32_e32 vcc, v53, v179
	v_sub_u32_e32 v53, v53, v179
	v_sub_u32_e32 v65, 0, v53
	v_max_i32_e32 v53, v53, v65
	v_cvt_f32_u32_e32 v53, v53
	v_cndmask_b32_e32 v65, v171, v170, vcc
	v_mul_f32_e32 v53, v65, v53
	v_exp_f32_e32 v65, v53
	v_sub_u32_e32 v53, v59, v179
	v_pk_mul_f32 v[36:37], v[64:65], v[36:37]
	s_nop 0
	v_cvt_pk_bf16_f32 v35, v36, v37
	v_bitop3_b32 v36, v63, v168, 15 bitop3:0x78
	v_lshl_add_u32 v36, v36, 4, v0
	ds_write_b64 v36, v[34:35]
	v_add_u32_e32 v34, 8, v54
	v_cmp_gt_i32_e32 vcc, v34, v179
	v_sub_u32_e32 v34, v34, v179
	v_sub_u32_e32 v35, 0, v34
	v_max_i32_e32 v34, v34, v35
	v_cvt_f32_u32_e32 v34, v34
	v_cndmask_b32_e32 v35, v171, v170, vcc
	v_mul_f32_e32 v34, v35, v34
	v_add_u32_e32 v35, 9, v54
	v_cmp_gt_i32_e32 vcc, v35, v179
	v_sub_u32_e32 v35, v35, v179
	v_sub_u32_e32 v36, 0, v35
	v_max_i32_e32 v35, v35, v36
	v_cvt_f32_u32_e32 v35, v35
	v_cndmask_b32_e32 v36, v171, v170, vcc
	v_exp_f32_e32 v34, v34
	v_mul_f32_e32 v35, v36, v35
	v_add_u32_e32 v36, 10, v54
	v_cmp_gt_i32_e32 vcc, v36, v179
	v_sub_u32_e32 v36, v36, v179
	v_sub_u32_e32 v37, 0, v36
	v_max_i32_e32 v36, v36, v37
	v_cvt_f32_u32_e32 v36, v36
	v_exp_f32_e32 v35, v35
	v_cndmask_b32_e32 v37, v171, v170, vcc
	v_mul_f32_e32 v36, v37, v36
	v_add_u32_e32 v37, 11, v54
	v_cmp_gt_i32_e32 vcc, v37, v179
	v_sub_u32_e32 v37, v37, v179
	v_pk_mul_f32 v[34:35], v[34:35], v[38:39]
	v_sub_u32_e32 v38, 0, v37
	v_max_i32_e32 v37, v37, v38
	v_cvt_f32_u32_e32 v37, v37
	v_cndmask_b32_e32 v38, v171, v170, vcc
	v_exp_f32_e32 v36, v36
	v_cvt_pk_bf16_f32 v34, v34, v35
	v_mul_f32_e32 v37, v38, v37
	v_exp_f32_e32 v37, v37
	s_nop 0
	v_pk_mul_f32 v[36:37], v[36:37], v[40:41]
	s_nop 0
	v_cvt_pk_bf16_f32 v35, v36, v37
	v_bitop3_b32 v36, v62, v168, 15 bitop3:0x78
	v_lshl_add_u32 v36, v36, 4, v0
	ds_write_b64 v36, v[34:35]
	v_add_u32_e32 v34, 16, v54
	v_cmp_gt_i32_e32 vcc, v34, v179
	v_sub_u32_e32 v34, v34, v179
	v_sub_u32_e32 v35, 0, v34
	v_max_i32_e32 v34, v34, v35
	v_cvt_f32_u32_e32 v34, v34
	v_cndmask_b32_e32 v35, v171, v170, vcc
	v_mul_f32_e32 v34, v35, v34
	v_add_u32_e32 v35, 17, v54
	v_cmp_gt_i32_e32 vcc, v35, v179
	v_sub_u32_e32 v35, v35, v179
	v_sub_u32_e32 v36, 0, v35
	v_max_i32_e32 v35, v35, v36
	v_cvt_f32_u32_e32 v35, v35
	v_cndmask_b32_e32 v36, v171, v170, vcc
	v_exp_f32_e32 v34, v34
	v_mul_f32_e32 v35, v36, v35
	v_add_u32_e32 v36, 18, v54
	v_cmp_gt_i32_e32 vcc, v36, v179
	v_sub_u32_e32 v36, v36, v179
	v_sub_u32_e32 v37, 0, v36
	v_max_i32_e32 v36, v36, v37
	v_cvt_f32_u32_e32 v36, v36
	v_cndmask_b32_e32 v37, v171, v170, vcc
	v_exp_f32_e32 v35, v35
	v_mul_f32_e32 v36, v37, v36
	v_add_u32_e32 v37, 19, v54
	v_cmp_gt_i32_e32 vcc, v37, v179
	v_sub_u32_e32 v37, v37, v179
	v_sub_u32_e32 v38, 0, v37
	v_max_i32_e32 v37, v37, v38
	v_cvt_f32_u32_e32 v37, v37
	v_cndmask_b32_e32 v38, v171, v170, vcc
	v_exp_f32_e32 v36, v36
	v_pk_mul_f32 v[34:35], v[34:35], v[42:43]
	v_mul_f32_e32 v37, v38, v37
	v_exp_f32_e32 v37, v37
	v_cvt_pk_bf16_f32 v34, v34, v35
	v_pk_mul_f32 v[36:37], v[36:37], v[44:45]
	s_nop 0
	v_cvt_pk_bf16_f32 v35, v36, v37
	v_bitop3_b32 v36, v61, v168, 15 bitop3:0x78
	v_lshl_add_u32 v36, v36, 4, v0
	ds_write_b64 v36, v[34:35]
	v_add_u32_e32 v34, 24, v54
	v_cmp_gt_i32_e32 vcc, v34, v179
	v_sub_u32_e32 v34, v34, v179
	v_sub_u32_e32 v35, 0, v34
	v_max_i32_e32 v34, v34, v35
	v_cvt_f32_u32_e32 v34, v34
	v_cndmask_b32_e32 v35, v171, v170, vcc
	v_mul_f32_e32 v34, v35, v34
	v_add_u32_e32 v35, 25, v54
	v_cmp_gt_i32_e32 vcc, v35, v179
	v_sub_u32_e32 v35, v35, v179
	v_sub_u32_e32 v36, 0, v35
; DI unsigned pack2(float a, float b) { f32x2_t v = {a, b}; bf16x2_t r = __builtin_convertvector(v, bf16x2_t); return __builtin_bit_cast(unsigned, r); }
; DI void retention_item(const Params& p, int l, bool ctx_out, int item2, char* smem) {
;     ...
; #pragma unroll
;         for (int q = 0; q < 4; ++q) {
;           float o[4];
; #pragma unroll
;           for (int j = 0; j < 4; ++j) {
;             const int m = mt * 32 + 8 * q + 4 * h5 + j;
;             const float dd = (m <= n) ? __builtin_amdgcn_exp2f(lgf2 * (float)(n - m)) : __builtin_amdgcn_exp2f(lgb2 * (float)(m - n));
;             o[j] = a[4 * q + j] * dd;
;           }
;           const int m0 = mt * 32 + 8 * q + 4 * h5;
;           *(u32x2*)(att + n * 256 + ((((m0 >> 3) ^ (n & 15)) << 4) | ((m0 & 7) << 1))) = mk2(pack2(o[0], o[1]), pack2(o[2], o[3]));
;         }
	v_max_i32_e32 v35, v35, v36
	v_cvt_f32_u32_e32 v35, v35
	v_cndmask_b32_e32 v36, v171, v170, vcc
	v_exp_f32_e32 v34, v34
	v_mul_f32_e32 v35, v36, v35
	v_add_u32_e32 v36, 26, v54
	v_cmp_gt_i32_e32 vcc, v36, v179
	v_sub_u32_e32 v36, v36, v179
	v_sub_u32_e32 v37, 0, v36
	v_max_i32_e32 v36, v36, v37
	v_cvt_f32_u32_e32 v36, v36
	v_cndmask_b32_e32 v37, v171, v170, vcc
	v_exp_f32_e32 v35, v35
	v_mul_f32_e32 v36, v37, v36
	v_add_u32_e32 v37, 27, v54
	v_cmp_gt_i32_e32 vcc, v37, v179
	v_sub_u32_e32 v37, v37, v179
	v_sub_u32_e32 v38, 0, v37
	v_max_i32_e32 v37, v37, v38
	v_cvt_f32_u32_e32 v37, v37
	v_cndmask_b32_e32 v38, v171, v170, vcc
	v_exp_f32_e32 v36, v36
	v_pk_mul_f32 v[34:35], v[34:35], v[46:47]
	v_mul_f32_e32 v37, v38, v37
	v_exp_f32_e32 v37, v37
	v_cvt_pk_bf16_f32 v34, v34, v35
	v_cmp_gt_i32_e32 vcc, v59, v179
	v_sub_u32_e32 v59, 0, v53
	v_pk_mul_f32 v[36:37], v[36:37], v[48:49]
	v_max_i32_e32 v53, v53, v59
	v_cvt_pk_bf16_f32 v35, v36, v37
	v_bitop3_b32 v36, v60, v168, 15 bitop3:0x78
	v_lshl_add_u32 v36, v36, 4, v0
	ds_write_b64 v36, v[34:35]
	v_or_b32_e32 v34, 32, v52
	v_ashrrev_i32_e32 v35, 31, v34
	v_lshlrev_b64 v[34:35], 11, v[34:35]
	v_lshl_add_u64 v[34:35], s[42:43], 0, v[34:35]
	v_lshl_add_u64 v[64:65], v[34:35], 0, v[50:51]
	global_load_dwordx4 v[34:37], v[64:65], off offset:1024
	global_load_dwordx4 v[60:63], v[64:65], off offset:1056
	v_cvt_f32_u32_e32 v53, v53
	v_cndmask_b32_e32 v59, v171, v170, vcc
	s_waitcnt vmcnt(1)
	v_mfma_f32_32x32x16_bf16 v[34:49], v[34:37], v[114:117], 0
	v_mul_f32_e32 v53, v59, v53
	s_waitcnt vmcnt(0)
	v_mfma_f32_32x32x16_bf16 v[34:49], v[60:63], v[118:121], v[34:49]
	global_load_dwordx4 v[60:63], v[64:65], off offset:1088
	s_waitcnt vmcnt(0)
	v_mfma_f32_32x32x16_bf16 v[34:49], v[60:63], v[122:125], v[34:49]
	global_load_dwordx4 v[60:63], v[64:65], off offset:1120
	s_waitcnt vmcnt(0)
	v_mfma_f32_32x32x16_bf16 v[34:49], v[60:63], v[126:129], v[34:49]
	v_exp_f32_e32 v60, v53
	v_add_u32_e32 v53, 33, v54
	v_cmp_gt_i32_e32 vcc, v53, v179
	v_sub_u32_e32 v53, v53, v179
	v_sub_u32_e32 v59, 0, v53
	v_max_i32_e32 v53, v53, v59
	v_cvt_f32_u32_e32 v53, v53
	v_cndmask_b32_e32 v59, v171, v170, vcc
	v_mul_f32_e32 v53, v59, v53
	v_exp_f32_e32 v61, v53
	v_add_u32_e32 v53, 34, v54
	v_cmp_gt_i32_e32 vcc, v53, v179
	v_sub_u32_e32 v53, v53, v179
	v_sub_u32_e32 v59, 0, v53
	v_max_i32_e32 v53, v53, v59
	v_cvt_f32_u32_e32 v53, v53
	v_cndmask_b32_e32 v59, v171, v170, vcc
	v_pk_mul_f32 v[34:35], v[60:61], v[34:35]
	v_mul_f32_e32 v53, v59, v53
	v_exp_f32_e32 v60, v53
	v_add_u32_e32 v53, 35, v54
	v_cmp_gt_i32_e32 vcc, v53, v179
	v_sub_u32_e32 v53, v53, v179
	v_sub_u32_e32 v59, 0, v53
	v_max_i32_e32 v53, v53, v59
	v_cvt_f32_u32_e32 v53, v53
	v_cndmask_b32_e32 v59, v171, v170, vcc
	v_cvt_pk_bf16_f32 v34, v34, v35
	v_mul_f32_e32 v53, v59, v53
	v_exp_f32_e32 v61, v53
	v_add_u32_e32 v53, 64, v54
	v_pk_mul_f32 v[36:37], v[60:61], v[36:37]
	s_nop 0
	v_cvt_pk_bf16_f32 v35, v36, v37
	v_bitop3_b32 v36, v58, v168, 15 bitop3:0x78
	v_lshl_add_u32 v36, v36, 4, v0
	ds_write_b64 v36, v[34:35]
	v_add_u32_e32 v34, 40, v54
	v_cmp_gt_i32_e32 vcc, v34, v179
	v_sub_u32_e32 v34, v34, v179
	v_sub_u32_e32 v35, 0, v34
	v_max_i32_e32 v34, v34, v35
	v_cvt_f32_u32_e32 v34, v34
	v_cndmask_b32_e32 v35, v171, v170, vcc
	v_mul_f32_e32 v34, v35, v34
	v_add_u32_e32 v35, 41, v54
	v_cmp_gt_i32_e32 vcc, v35, v179
	v_sub_u32_e32 v35, v35, v179
	v_sub_u32_e32 v36, 0, v35
	v_max_i32_e32 v35, v35, v36
	v_cvt_f32_u32_e32 v35, v35
	v_cndmask_b32_e32 v36, v171, v170, vcc
	v_exp_f32_e32 v34, v34
	v_mul_f32_e32 v35, v36, v35
	v_add_u32_e32 v36, 42, v54
	v_cmp_gt_i32_e32 vcc, v36, v179
	v_sub_u32_e32 v36, v36, v179
	v_sub_u32_e32 v37, 0, v36
	v_max_i32_e32 v36, v36, v37
	v_cvt_f32_u32_e32 v36, v36
	v_exp_f32_e32 v35, v35
	v_cndmask_b32_e32 v37, v171, v170, vcc
	v_mul_f32_e32 v36, v37, v36
	v_add_u32_e32 v37, 43, v54
	v_cmp_gt_i32_e32 vcc, v37, v179
	v_sub_u32_e32 v37, v37, v179
	v_pk_mul_f32 v[34:35], v[34:35], v[38:39]
	v_sub_u32_e32 v38, 0, v37
	v_max_i32_e32 v37, v37, v38
	v_cvt_f32_u32_e32 v37, v37
	v_cndmask_b32_e32 v38, v171, v170, vcc
	v_exp_f32_e32 v36, v36
	v_cvt_pk_bf16_f32 v34, v34, v35
	v_mul_f32_e32 v37, v38, v37
	v_exp_f32_e32 v37, v37
	s_nop 0
	v_pk_mul_f32 v[36:37], v[36:37], v[40:41]
	s_nop 0
	v_cvt_pk_bf16_f32 v35, v36, v37
	v_bitop3_b32 v36, v57, v168, 15 bitop3:0x78
	v_lshl_add_u32 v36, v36, 4, v0
	ds_write_b64 v36, v[34:35]
	v_add_u32_e32 v34, 48, v54
	v_cmp_gt_i32_e32 vcc, v34, v179
	v_sub_u32_e32 v34, v34, v179
	v_sub_u32_e32 v35, 0, v34
	v_max_i32_e32 v34, v34, v35
	v_cvt_f32_u32_e32 v34, v34
	v_cndmask_b32_e32 v35, v171, v170, vcc
	v_mul_f32_e32 v34, v35, v34
	v_add_u32_e32 v35, 49, v54
	v_cmp_gt_i32_e32 vcc, v35, v179
	v_sub_u32_e32 v35, v35, v179
	v_sub_u32_e32 v36, 0, v35
	v_max_i32_e32 v35, v35, v36
	v_cvt_f32_u32_e32 v35, v35
	v_cndmask_b32_e32 v36, v171, v170, vcc
	v_exp_f32_e32 v34, v34
	v_mul_f32_e32 v35, v36, v35
	v_add_u32_e32 v36, 50, v54
	v_cmp_gt_i32_e32 vcc, v36, v179
	v_sub_u32_e32 v36, v36, v179
	v_sub_u32_e32 v37, 0, v36
	v_max_i32_e32 v36, v36, v37
	v_cvt_f32_u32_e32 v36, v36
	v_cndmask_b32_e32 v37, v171, v170, vcc
	v_exp_f32_e32 v35, v35
	v_mul_f32_e32 v36, v37, v36
	v_add_u32_e32 v37, 51, v54
	v_cmp_gt_i32_e32 vcc, v37, v179
	v_sub_u32_e32 v37, v37, v179
	v_sub_u32_e32 v38, 0, v37
	v_max_i32_e32 v37, v37, v38
	v_cvt_f32_u32_e32 v37, v37
	v_cndmask_b32_e32 v38, v171, v170, vcc
	v_exp_f32_e32 v36, v36
	v_pk_mul_f32 v[34:35], v[34:35], v[42:43]
	v_mul_f32_e32 v37, v38, v37
	v_exp_f32_e32 v37, v37
	v_cvt_pk_bf16_f32 v34, v34, v35
	v_pk_mul_f32 v[36:37], v[36:37], v[44:45]
	s_nop 0
	v_cvt_pk_bf16_f32 v35, v36, v37
	v_bitop3_b32 v36, v56, v168, 15 bitop3:0x78
; DI unsigned pack2(float a, float b) { f32x2_t v = {a, b}; bf16x2_t r = __builtin_convertvector(v, bf16x2_t); return __builtin_bit_cast(unsigned, r); }
; DI void retention_item(const Params& p, int l, bool ctx_out, int item2, char* smem) {
;     ...
; #pragma unroll
;         for (int q = 0; q < 4; ++q) {
;           float o[4];
; #pragma unroll
;           for (int j = 0; j < 4; ++j) {
;             const int m = mt * 32 + 8 * q + 4 * h5 + j;
;             const float dd = (m <= n) ? __builtin_amdgcn_exp2f(lgf2 * (float)(n - m)) : __builtin_amdgcn_exp2f(lgb2 * (float)(m - n));
;             o[j] = a[4 * q + j] * dd;
;           }
;           const int m0 = mt * 32 + 8 * q + 4 * h5;
;           *(u32x2*)(att + n * 256 + ((((m0 >> 3) ^ (n & 15)) << 4) | ((m0 & 7) << 1))) = mk2(pack2(o[0], o[1]), pack2(o[2], o[3]));
;         }
	v_lshl_add_u32 v36, v36, 4, v0
	ds_write_b64 v36, v[34:35]
	v_add_u32_e32 v34, 56, v54
	v_cmp_gt_i32_e32 vcc, v34, v179
	v_sub_u32_e32 v34, v34, v179
	v_sub_u32_e32 v35, 0, v34
	v_max_i32_e32 v34, v34, v35
	v_cvt_f32_u32_e32 v34, v34
	v_cndmask_b32_e32 v35, v171, v170, vcc
	v_mul_f32_e32 v34, v35, v34
	v_add_u32_e32 v35, 57, v54
	v_cmp_gt_i32_e32 vcc, v35, v179
	v_sub_u32_e32 v35, v35, v179
	v_sub_u32_e32 v36, 0, v35
	v_max_i32_e32 v35, v35, v36
	v_cvt_f32_u32_e32 v35, v35
	v_cndmask_b32_e32 v36, v171, v170, vcc
	v_exp_f32_e32 v34, v34
	v_mul_f32_e32 v35, v36, v35
	v_add_u32_e32 v36, 58, v54
	v_cmp_gt_i32_e32 vcc, v36, v179
	v_sub_u32_e32 v36, v36, v179
	v_sub_u32_e32 v37, 0, v36
	v_max_i32_e32 v36, v36, v37
	v_cvt_f32_u32_e32 v36, v36
	v_cndmask_b32_e32 v37, v171, v170, vcc
	v_exp_f32_e32 v35, v35
	v_mul_f32_e32 v36, v37, v36
	v_add_u32_e32 v37, 59, v54
	v_cmp_gt_i32_e32 vcc, v37, v179
	v_sub_u32_e32 v37, v37, v179
	v_sub_u32_e32 v38, 0, v37
	v_max_i32_e32 v37, v37, v38
	v_cvt_f32_u32_e32 v37, v37
	v_cndmask_b32_e32 v38, v171, v170, vcc
	v_exp_f32_e32 v36, v36
	v_pk_mul_f32 v[34:35], v[34:35], v[46:47]
	v_mul_f32_e32 v37, v38, v37
	v_exp_f32_e32 v37, v37
	v_cvt_pk_bf16_f32 v34, v34, v35
	v_cmp_gt_i32_e32 vcc, v53, v179
	v_pk_mul_f32 v[36:37], v[36:37], v[48:49]
	s_nop 0
	v_cvt_pk_bf16_f32 v35, v36, v37
	v_bitop3_b32 v36, v55, v168, 15 bitop3:0x78
	v_lshl_add_u32 v36, v36, 4, v0
	ds_write_b64 v36, v[34:35]
	v_or_b32_e32 v34, 64, v52
	v_ashrrev_i32_e32 v35, 31, v34
	v_lshlrev_b64 v[34:35], 11, v[34:35]
	v_lshl_add_u64 v[34:35], s[42:43], 0, v[34:35]
	v_lshl_add_u64 v[60:61], v[34:35], 0, v[50:51]
	global_load_dwordx4 v[34:37], v[60:61], off offset:1024
	global_load_dwordx4 v[56:59], v[60:61], off offset:1056
	s_waitcnt vmcnt(1)
	v_mfma_f32_32x32x16_bf16 v[34:49], v[34:37], v[114:117], 0
	v_sub_u32_e32 v55, v53, v179
	v_lshrrev_b32_e32 v53, 3, v53
	s_waitcnt vmcnt(0)
	v_mfma_f32_32x32x16_bf16 v[34:49], v[56:59], v[118:121], v[34:49]
	global_load_dwordx4 v[56:59], v[60:61], off offset:1088
	s_waitcnt vmcnt(0)
	v_mfma_f32_32x32x16_bf16 v[34:49], v[56:59], v[122:125], v[34:49]
	global_load_dwordx4 v[56:59], v[60:61], off offset:1120
	s_waitcnt vmcnt(0)
	v_mfma_f32_32x32x16_bf16 v[34:49], v[56:59], v[126:129], v[34:49]
	v_sub_u32_e32 v56, 0, v55
	v_max_i32_e32 v55, v55, v56
	v_cvt_f32_u32_e32 v55, v55
	v_cndmask_b32_e32 v56, v171, v170, vcc
	v_mul_f32_e32 v55, v56, v55
	v_exp_f32_e32 v56, v55
	v_add_u32_e32 v55, 0x41, v54
	v_cmp_gt_i32_e32 vcc, v55, v179
	v_sub_u32_e32 v55, v55, v179
	v_sub_u32_e32 v57, 0, v55
	v_max_i32_e32 v55, v55, v57
	v_cvt_f32_u32_e32 v55, v55
	v_cndmask_b32_e32 v57, v171, v170, vcc
	v_mul_f32_e32 v55, v57, v55
	v_exp_f32_e32 v57, v55
	v_add_u32_e32 v55, 0x42, v54
	v_cmp_gt_i32_e32 vcc, v55, v179
	v_sub_u32_e32 v55, v55, v179
	v_pk_mul_f32 v[34:35], v[56:57], v[34:35]
	v_sub_u32_e32 v56, 0, v55
	v_max_i32_e32 v55, v55, v56
	v_cvt_f32_u32_e32 v55, v55
	v_cndmask_b32_e32 v56, v171, v170, vcc
	v_cvt_pk_bf16_f32 v34, v34, v35
	v_mul_f32_e32 v55, v56, v55
	v_exp_f32_e32 v56, v55
	v_add_u32_e32 v55, 0x43, v54
	v_cmp_gt_i32_e32 vcc, v55, v179
	v_sub_u32_e32 v55, v55, v179
	v_sub_u32_e32 v57, 0, v55
	v_max_i32_e32 v55, v55, v57
	v_cvt_f32_u32_e32 v55, v55
	v_cndmask_b32_e32 v57, v171, v170, vcc
	v_mul_f32_e32 v55, v57, v55
	v_exp_f32_e32 v57, v55
	s_nop 0
	v_pk_mul_f32 v[36:37], v[56:57], v[36:37]
	s_nop 0
	v_cvt_pk_bf16_f32 v35, v36, v37
	v_bitop3_b32 v36, v53, v168, 15 bitop3:0x78
	v_lshl_add_u32 v36, v36, 4, v0
	ds_write_b64 v36, v[34:35]
	v_add_u32_e32 v34, 0x48, v54
	v_cmp_gt_i32_e32 vcc, v34, v179
	v_sub_u32_e32 v34, v34, v179
	v_sub_u32_e32 v35, 0, v34
	v_max_i32_e32 v34, v34, v35
	v_cvt_f32_u32_e32 v34, v34
	v_cndmask_b32_e32 v35, v171, v170, vcc
	v_mul_f32_e32 v34, v35, v34
	v_add_u32_e32 v35, 0x49, v54
	v_cmp_gt_i32_e32 vcc, v35, v179
	v_sub_u32_e32 v35, v35, v179
	v_sub_u32_e32 v36, 0, v35
	v_max_i32_e32 v35, v35, v36
	v_cvt_f32_u32_e32 v35, v35
	v_cndmask_b32_e32 v36, v171, v170, vcc
	v_exp_f32_e32 v34, v34
	v_mul_f32_e32 v35, v36, v35
	v_add_u32_e32 v36, 0x4a, v54
	v_cmp_gt_i32_e32 vcc, v36, v179
	v_sub_u32_e32 v36, v36, v179
	v_sub_u32_e32 v37, 0, v36
	v_max_i32_e32 v36, v36, v37
	v_cvt_f32_u32_e32 v36, v36
	v_exp_f32_e32 v35, v35
	v_cndmask_b32_e32 v37, v171, v170, vcc
	v_mul_f32_e32 v36, v37, v36
	v_add_u32_e32 v37, 0x4b, v54
	v_cmp_gt_i32_e32 vcc, v37, v179
	v_sub_u32_e32 v37, v37, v179
	v_pk_mul_f32 v[34:35], v[34:35], v[38:39]
	v_sub_u32_e32 v38, 0, v37
	v_max_i32_e32 v37, v37, v38
	v_cvt_f32_u32_e32 v37, v37
	v_cndmask_b32_e32 v38, v171, v170, vcc
	v_exp_f32_e32 v36, v36
	v_cvt_pk_bf16_f32 v34, v34, v35
	v_mul_f32_e32 v37, v38, v37
	v_exp_f32_e32 v37, v37
	s_nop 0
	v_pk_mul_f32 v[36:37], v[36:37], v[40:41]
	s_nop 0
	v_cvt_pk_bf16_f32 v35, v36, v37
	v_add_u32_e32 v36, 1, v53
	v_bitop3_b32 v36, v36, v168, 15 bitop3:0x78
	v_lshl_add_u32 v36, v36, 4, v0
	ds_write_b64 v36, v[34:35]
	v_add_u32_e32 v34, 0x50, v54
	v_cmp_gt_i32_e32 vcc, v34, v179
	v_sub_u32_e32 v34, v34, v179
	v_sub_u32_e32 v35, 0, v34
	v_max_i32_e32 v34, v34, v35
	v_cvt_f32_u32_e32 v34, v34
	v_cndmask_b32_e32 v35, v171, v170, vcc
	v_mul_f32_e32 v34, v35, v34
	v_add_u32_e32 v35, 0x51, v54
	v_cmp_gt_i32_e32 vcc, v35, v179
	v_sub_u32_e32 v35, v35, v179
	v_sub_u32_e32 v36, 0, v35
	v_max_i32_e32 v35, v35, v36
	v_cvt_f32_u32_e32 v35, v35
	v_cndmask_b32_e32 v36, v171, v170, vcc
	v_exp_f32_e32 v34, v34
	v_mul_f32_e32 v35, v36, v35
	v_add_u32_e32 v36, 0x52, v54
	v_cmp_gt_i32_e32 vcc, v36, v179
	v_sub_u32_e32 v36, v36, v179
	v_sub_u32_e32 v37, 0, v36
	v_max_i32_e32 v36, v36, v37
	v_cvt_f32_u32_e32 v36, v36
	v_cndmask_b32_e32 v37, v171, v170, vcc
; DI unsigned pack2(float a, float b) { f32x2_t v = {a, b}; bf16x2_t r = __builtin_convertvector(v, bf16x2_t); return __builtin_bit_cast(unsigned, r); }
; DI void retention_item(const Params& p, int l, bool ctx_out, int item2, char* smem) {
;     ...
; #pragma unroll
;         for (int q = 0; q < 4; ++q) {
;           float o[4];
; #pragma unroll
;           for (int j = 0; j < 4; ++j) {
;             const int m = mt * 32 + 8 * q + 4 * h5 + j;
;             const float dd = (m <= n) ? __builtin_amdgcn_exp2f(lgf2 * (float)(n - m)) : __builtin_amdgcn_exp2f(lgb2 * (float)(m - n));
;             o[j] = a[4 * q + j] * dd;
;           }
;           const int m0 = mt * 32 + 8 * q + 4 * h5;
;           *(u32x2*)(att + n * 256 + ((((m0 >> 3) ^ (n & 15)) << 4) | ((m0 & 7) << 1))) = mk2(pack2(o[0], o[1]), pack2(o[2], o[3]));
;         }
	v_exp_f32_e32 v35, v35
	v_mul_f32_e32 v36, v37, v36
	v_add_u32_e32 v37, 0x53, v54
	v_cmp_gt_i32_e32 vcc, v37, v179
	v_sub_u32_e32 v37, v37, v179
	v_sub_u32_e32 v38, 0, v37
	v_max_i32_e32 v37, v37, v38
	v_cvt_f32_u32_e32 v37, v37
	v_cndmask_b32_e32 v38, v171, v170, vcc
	v_exp_f32_e32 v36, v36
	v_pk_mul_f32 v[34:35], v[34:35], v[42:43]
	v_mul_f32_e32 v37, v38, v37
	v_exp_f32_e32 v37, v37
	v_cvt_pk_bf16_f32 v34, v34, v35
	v_pk_mul_f32 v[36:37], v[36:37], v[44:45]
	s_nop 0
	v_cvt_pk_bf16_f32 v35, v36, v37
	v_add_u32_e32 v36, 2, v53
	v_bitop3_b32 v36, v36, v168, 15 bitop3:0x78
	v_lshl_add_u32 v36, v36, 4, v0
	ds_write_b64 v36, v[34:35]
	v_add_u32_e32 v34, 0x58, v54
	v_cmp_gt_i32_e32 vcc, v34, v179
	v_sub_u32_e32 v34, v34, v179
	v_sub_u32_e32 v35, 0, v34
	v_max_i32_e32 v34, v34, v35
	v_cvt_f32_u32_e32 v34, v34
	v_cndmask_b32_e32 v35, v171, v170, vcc
	v_mul_f32_e32 v34, v35, v34
	v_add_u32_e32 v35, 0x59, v54
	v_cmp_gt_i32_e32 vcc, v35, v179
	v_sub_u32_e32 v35, v35, v179
	v_sub_u32_e32 v36, 0, v35
	v_max_i32_e32 v35, v35, v36
	v_cvt_f32_u32_e32 v35, v35
	v_cndmask_b32_e32 v36, v171, v170, vcc
	v_exp_f32_e32 v34, v34
	v_mul_f32_e32 v35, v36, v35
	v_add_u32_e32 v36, 0x5a, v54
	v_cmp_gt_i32_e32 vcc, v36, v179
	v_sub_u32_e32 v36, v36, v179
	v_sub_u32_e32 v37, 0, v36
	v_max_i32_e32 v36, v36, v37
	v_cvt_f32_u32_e32 v36, v36
	v_cndmask_b32_e32 v37, v171, v170, vcc
	v_exp_f32_e32 v35, v35
	v_mul_f32_e32 v36, v37, v36
	v_add_u32_e32 v37, 0x5b, v54
	v_cmp_gt_i32_e32 vcc, v37, v179
	v_sub_u32_e32 v37, v37, v179
	v_sub_u32_e32 v38, 0, v37
	v_max_i32_e32 v37, v37, v38
	v_cvt_f32_u32_e32 v37, v37
	v_cndmask_b32_e32 v38, v171, v170, vcc
	v_exp_f32_e32 v36, v36
	v_pk_mul_f32 v[34:35], v[34:35], v[46:47]
	v_mul_f32_e32 v37, v38, v37
	v_exp_f32_e32 v37, v37
	v_cvt_pk_bf16_f32 v34, v34, v35
	v_pk_mul_f32 v[36:37], v[36:37], v[48:49]
	s_nop 0
	v_cvt_pk_bf16_f32 v35, v36, v37
	v_add_u32_e32 v36, 3, v53
	v_bitop3_b32 v36, v36, v168, 15 bitop3:0x78
	v_lshl_add_u32 v36, v36, 4, v0
	ds_write_b64 v36, v[34:35]
	v_or_b32_e32 v34, 0x60, v52
	v_ashrrev_i32_e32 v35, 31, v34
	v_lshlrev_b64 v[34:35], 11, v[34:35]
	v_lshl_add_u64 v[34:35], s[42:43], 0, v[34:35]
	v_lshl_add_u64 v[56:57], v[34:35], 0, v[50:51]
	global_load_dwordx4 v[34:37], v[56:57], off offset:1024
	global_load_dwordx4 v[50:53], v[56:57], off offset:1056
	s_waitcnt vmcnt(1)
	v_mfma_f32_32x32x16_bf16 v[34:49], v[34:37], v[114:117], 0
	s_waitcnt vmcnt(0)
	v_mfma_f32_32x32x16_bf16 v[34:49], v[50:53], v[118:121], v[34:49]
	global_load_dwordx4 v[50:53], v[56:57], off offset:1088
	s_waitcnt vmcnt(0)
	v_mfma_f32_32x32x16_bf16 v[34:49], v[50:53], v[122:125], v[34:49]
	global_load_dwordx4 v[50:53], v[56:57], off offset:1120
	s_waitcnt vmcnt(0)
; DI unsigned pack2(float a, float b) { f32x2_t v = {a, b}; bf16x2_t r = __builtin_convertvector(v, bf16x2_t); return __builtin_bit_cast(unsigned, r); }
; DI void retention_item(const Params& p, int l, bool ctx_out, int item2, char* smem) {
;     ...
; #pragma unroll
;         for (int q = 0; q < 4; ++q) {
;           float o[4];
; #pragma unroll
;           for (int j = 0; j < 4; ++j) {
;             const int m = mt * 32 + 8 * q + 4 * h5 + j;
;             const float dd = (m <= n) ? __builtin_amdgcn_exp2f(lgf2 * (float)(n - m)) : __builtin_amdgcn_exp2f(lgb2 * (float)(m - n));
;             o[j] = a[4 * q + j] * dd;
;           }
;           const int m0 = mt * 32 + 8 * q + 4 * h5;
;           *(u32x2*)(att + n * 256 + ((((m0 >> 3) ^ (n & 15)) << 4) | ((m0 & 7) << 1))) = mk2(pack2(o[0], o[1]), pack2(o[2], o[3]));
;         }
	v_mfma_f32_32x32x16_bf16 v[34:49], v[50:53], v[126:129], v[34:49]
	v_add_u32_e32 v52, 0x60, v54
	v_sub_u32_e32 v50, v52, v179
	v_sub_u32_e32 v51, 0, v50
	v_max_i32_e32 v50, v50, v51
	v_cvt_f32_u32_e32 v50, v50
	v_cmp_gt_i32_e32 vcc, v52, v179
	s_nop 1
	v_cndmask_b32_e32 v51, v171, v170, vcc
	v_mul_f32_e32 v50, v51, v50
	v_add_u32_e32 v51, 0x61, v54
	v_cmp_gt_i32_e32 vcc, v51, v179
	v_sub_u32_e32 v51, v51, v179
	v_sub_u32_e32 v53, 0, v51
	v_max_i32_e32 v51, v51, v53
	v_cvt_f32_u32_e32 v51, v51
	v_cndmask_b32_e32 v53, v171, v170, vcc
	v_exp_f32_e32 v50, v50
	v_mul_f32_e32 v51, v53, v51
	v_exp_f32_e32 v51, v51
	s_nop 0
	v_pk_mul_f32 v[34:35], v[50:51], v[34:35]
	v_add_u32_e32 v50, 0x62, v54
	v_cmp_gt_i32_e32 vcc, v50, v179
	v_sub_u32_e32 v50, v50, v179
	v_sub_u32_e32 v51, 0, v50
	v_max_i32_e32 v50, v50, v51
	v_cvt_f32_u32_e32 v50, v50
	v_cndmask_b32_e32 v51, v171, v170, vcc
	v_cvt_pk_bf16_f32 v34, v34, v35
	v_mul_f32_e32 v50, v51, v50
	v_add_u32_e32 v51, 0x63, v54
	v_cmp_gt_i32_e32 vcc, v51, v179
	v_sub_u32_e32 v51, v51, v179
	v_sub_u32_e32 v53, 0, v51
	v_max_i32_e32 v51, v51, v53
	v_cvt_f32_u32_e32 v51, v51
	v_cndmask_b32_e32 v53, v171, v170, vcc
	v_exp_f32_e32 v50, v50
	v_mul_f32_e32 v51, v53, v51
	v_exp_f32_e32 v51, v51
	s_nop 0
	v_pk_mul_f32 v[36:37], v[50:51], v[36:37]
	v_lshrrev_b32_e32 v50, 3, v52
	v_cvt_pk_bf16_f32 v35, v36, v37
	v_bitop3_b32 v36, v50, v168, 15 bitop3:0x78
	v_lshl_add_u32 v36, v36, 4, v0
	ds_write_b64 v36, v[34:35]
	v_add_u32_e32 v34, 0x68, v54
	v_cmp_gt_i32_e32 vcc, v34, v179
	v_sub_u32_e32 v34, v34, v179
	v_sub_u32_e32 v35, 0, v34
	v_max_i32_e32 v34, v34, v35
	v_cvt_f32_u32_e32 v34, v34
	v_cndmask_b32_e32 v35, v171, v170, vcc
	v_mul_f32_e32 v34, v35, v34
	v_add_u32_e32 v35, 0x69, v54
	v_cmp_gt_i32_e32 vcc, v35, v179
	v_sub_u32_e32 v35, v35, v179
	v_sub_u32_e32 v36, 0, v35
	v_max_i32_e32 v35, v35, v36
	v_cvt_f32_u32_e32 v35, v35
	v_cndmask_b32_e32 v36, v171, v170, vcc
	v_exp_f32_e32 v34, v34
	v_mul_f32_e32 v35, v36, v35
	v_add_u32_e32 v36, 0x6a, v54
	v_cmp_gt_i32_e32 vcc, v36, v179
	v_sub_u32_e32 v36, v36, v179
	v_sub_u32_e32 v37, 0, v36
	v_max_i32_e32 v36, v36, v37
	v_cvt_f32_u32_e32 v36, v36
	v_exp_f32_e32 v35, v35
	v_cndmask_b32_e32 v37, v171, v170, vcc
	v_mul_f32_e32 v36, v37, v36
	v_add_u32_e32 v37, 0x6b, v54
	v_cmp_gt_i32_e32 vcc, v37, v179
	v_sub_u32_e32 v37, v37, v179
	v_pk_mul_f32 v[34:35], v[34:35], v[38:39]
	v_sub_u32_e32 v38, 0, v37
	v_max_i32_e32 v37, v37, v38
	v_cvt_f32_u32_e32 v37, v37
	v_cndmask_b32_e32 v38, v171, v170, vcc
	v_exp_f32_e32 v36, v36
	v_cvt_pk_bf16_f32 v34, v34, v35
	v_mul_f32_e32 v37, v38, v37
	v_exp_f32_e32 v37, v37
	s_nop 0
	v_pk_mul_f32 v[36:37], v[36:37], v[40:41]
	s_nop 0
	v_cvt_pk_bf16_f32 v35, v36, v37
	v_add_u32_e32 v36, 1, v50
	v_bitop3_b32 v36, v36, v168, 15 bitop3:0x78
	v_lshl_add_u32 v36, v36, 4, v0
	ds_write_b64 v36, v[34:35]
	v_add_u32_e32 v34, 0x70, v54
	v_cmp_gt_i32_e32 vcc, v34, v179
	v_sub_u32_e32 v34, v34, v179
	v_sub_u32_e32 v35, 0, v34
	v_max_i32_e32 v34, v34, v35
	v_cvt_f32_u32_e32 v34, v34
	v_cndmask_b32_e32 v35, v171, v170, vcc
	v_mul_f32_e32 v34, v35, v34
	v_add_u32_e32 v35, 0x71, v54
	v_cmp_gt_i32_e32 vcc, v35, v179
	v_sub_u32_e32 v35, v35, v179
	v_sub_u32_e32 v36, 0, v35
	v_max_i32_e32 v35, v35, v36
	v_cvt_f32_u32_e32 v35, v35
	v_cndmask_b32_e32 v36, v171, v170, vcc
	v_exp_f32_e32 v34, v34
	v_mul_f32_e32 v35, v36, v35
	v_add_u32_e32 v36, 0x72, v54
	v_cmp_gt_i32_e32 vcc, v36, v179
	v_sub_u32_e32 v36, v36, v179
	v_sub_u32_e32 v37, 0, v36
	v_max_i32_e32 v36, v36, v37
	v_cvt_f32_u32_e32 v36, v36
	v_cndmask_b32_e32 v37, v171, v170, vcc
	v_exp_f32_e32 v35, v35
	v_mul_f32_e32 v36, v37, v36
	v_add_u32_e32 v37, 0x73, v54
	v_cmp_gt_i32_e32 vcc, v37, v179
	v_sub_u32_e32 v37, v37, v179
	v_sub_u32_e32 v38, 0, v37
	v_max_i32_e32 v37, v37, v38
	v_cvt_f32_u32_e32 v37, v37
	v_cndmask_b32_e32 v38, v171, v170, vcc
	v_exp_f32_e32 v36, v36
	v_pk_mul_f32 v[34:35], v[34:35], v[42:43]
	v_mul_f32_e32 v37, v38, v37
	v_exp_f32_e32 v37, v37
	v_cvt_pk_bf16_f32 v34, v34, v35
	v_pk_mul_f32 v[36:37], v[36:37], v[44:45]
	s_nop 0
	v_cvt_pk_bf16_f32 v35, v36, v37
	v_add_u32_e32 v36, 2, v50
	v_bitop3_b32 v36, v36, v168, 15 bitop3:0x78
	v_lshl_add_u32 v36, v36, 4, v0
	ds_write_b64 v36, v[34:35]
	v_add_u32_e32 v34, 0x78, v54
	v_cmp_gt_i32_e32 vcc, v34, v179
	v_sub_u32_e32 v34, v34, v179
	v_sub_u32_e32 v35, 0, v34
	v_max_i32_e32 v34, v34, v35
	v_cvt_f32_u32_e32 v34, v34
	v_cndmask_b32_e32 v35, v171, v170, vcc
	v_mul_f32_e32 v34, v35, v34
	v_add_u32_e32 v35, 0x79, v54
	v_cmp_gt_i32_e32 vcc, v35, v179
	v_sub_u32_e32 v35, v35, v179
	v_sub_u32_e32 v36, 0, v35
	v_max_i32_e32 v35, v35, v36
	v_cvt_f32_u32_e32 v35, v35
	v_cndmask_b32_e32 v36, v171, v170, vcc
	v_exp_f32_e32 v34, v34
	v_mul_f32_e32 v35, v36, v35
	v_add_u32_e32 v36, 0x7a, v54
	v_cmp_gt_i32_e32 vcc, v36, v179
	v_sub_u32_e32 v36, v36, v179
	v_sub_u32_e32 v37, 0, v36
	v_max_i32_e32 v36, v36, v37
	v_cvt_f32_u32_e32 v36, v36
	v_cndmask_b32_e32 v37, v171, v170, vcc
	v_exp_f32_e32 v35, v35
	v_mul_f32_e32 v36, v37, v36
	v_add_u32_e32 v37, 0x7b, v54
	v_cmp_gt_i32_e32 vcc, v37, v179
	v_sub_u32_e32 v37, v37, v179
	v_sub_u32_e32 v38, 0, v37
	v_max_i32_e32 v37, v37, v38
	v_cvt_f32_u32_e32 v37, v37
	v_cndmask_b32_e32 v38, v171, v170, vcc
	v_exp_f32_e32 v36, v36
	v_pk_mul_f32 v[34:35], v[34:35], v[46:47]
	v_mul_f32_e32 v37, v38, v37
	v_exp_f32_e32 v37, v37
	v_cvt_pk_bf16_f32 v34, v34, v35
	v_pk_mul_f32 v[36:37], v[36:37], v[48:49]
	s_nop 0
	v_cvt_pk_bf16_f32 v35, v36, v37
	v_add_u32_e32 v36, 3, v50
	v_bitop3_b32 v36, v36, v168, 15 bitop3:0x78
	v_lshl_add_u32 v0, v36, 4, v0
	ds_write_b64 v0, v[34:35]
